# static wave priority + attention phase: s_setprio 3/0 around the QK^T and PV MFMA clusters (DUP x4 of the phase: -3.5 us per pass)
# baseline (speedup 1.0000x reference)
; template <int KB>
; __device__ __forceinline__ void qkt(f32x16& p0, f32x16& p1, const char* K_lds, int r32, int hi, const bf16x8* qs) {
;     p0 = f32x16{}; p1 = f32x16{};
;     const char* kb[4];
; #pragma unroll
;     for (int dd = 0; dd < 4; ++dd) kb[dd] = K_lds + KB * SHM_K + KSWZ(r32, (dd * 16 + hi * 8) * 2);
; #pragma unroll
;     for (int d0 = 0; d0 < 8; ++d0) { const char* a = kb[d0 & 3] + (d0 >> 2) * 128;
;         bf16x8 b0 = *reinterpret_cast<const bf16x8*>(a);
;         bf16x8 b1 = *reinterpret_cast<const bf16x8*>(a + 32 * 256);
;         const bf16x8 qf = qs[d0 * 64];
;         p0 = __builtin_amdgcn_mfma_f32_32x32x16_bf16(b0, qf, p0, 0, 0, 0);
;         p1 = __builtin_amdgcn_mfma_f32_32x32x16_bf16(b1, qf, p1, 0, 0, 0); }
; }
; template <int VB>
; __device__ __forceinline__ void pv_tile(f32x16* o, int vb0, bf16x8 pa0, bf16x8 pa1, bf16x8 pa2, bf16x8 pa3) {
;     ...
;     s16x4 Al0, Al1, Al2, Al3, Ah0, Ah1, Ah2, Ah3, Bl0, Bl1, Bl2, Bl3, Bh0, Bh1, Bh2, Bh3;
;     PV_RD(A, 0); PV_RD(B, 1); PV_WAIT(8); PV_MM(A, 0);
;     PV_RD(A, 2); PV_WAIT(8); PV_MM(B, 1);
;     PV_RD(B, 3); PV_WAIT(8); PV_MM(A, 2);
;     PV_WAIT(0); PV_MM(B, 3);
;     ...
; }
; __device__ __forceinline__ bf16x8 knorm8(bf16x8 x, const float* g) {
;     const v4u xv = __builtin_bit_cast(v4u, x); float f[8];
; #pragma unroll
;     for (int e = 0; e < 4; ++e) { f[2 * e] = __builtin_bit_cast(float, xv[e] << 16); f[2 * e + 1] = __builtin_bit_cast(float, xv[e] & 0xffff0000u); }
;     float s = 0.f;
; #pragma unroll
;     for (int e = 0; e < 8; ++e) s += f[e] * f[e];
;     s += __shfl_xor(s, 1); s += __shfl_xor(s, 2); s += __shfl_xor(s, 4); s += __shfl_xor(s, 8);
;     const float r = __builtin_amdgcn_rsqf(s * (1.0f / 128.0f) + 1e-6f);
;     const f32x4 g0 = *(const f32x4*)g, g1 = *(const f32x4*)(g + 4);
;     v4u w; w.x = cvtpk(f[0] * r * g0[0], f[1] * r * g0[1]); w.y = cvtpk(f[2] * r * g0[2], f[3] * r * g0[3]); w.z = cvtpk(f[4] * r * g1[0], f[5] * r * g1[1]); w.w = cvtpk(f[6] * r * g1[2], f[7] * r * g1[3]);
;     return __builtin_bit_cast(bf16x8, w);
; }
; template <int BUF>
; __device__ __forceinline__ void fox_tile(f32x16* o, float& m_reg, float& l_reg, const char* lds, const float* ckl, float* al_l, int vb0, const bf16x8* qr, float cq, int qpos, int kb0, bool need_mask, int r32, int hi) {
;     f32x16 p0, p1;
;     qkt<BUF>(p0, p1, lds + 2 * SHM_V, r32, hi, qr);
.LBB0_1335:
	ds_read_b128 v[80:83], v162 offset:288
	s_add_i32 s0, s72, 63
	s_cmp_le_i32 s0, s40
	s_waitcnt lgkmcnt(0)
	v_sub_f32_e32 v133, v69, v81
	v_sub_f32_e32 v132, v68, v80
	v_sub_f32_e32 v131, v71, v83
	v_sub_f32_e32 v130, v70, v82
	ds_read_b128 v[80:83], v162 offset:320
	s_waitcnt lgkmcnt(0)
	v_sub_f32_e32 v127, v73, v81
	v_sub_f32_e32 v126, v72, v80
	v_sub_f32_e32 v125, v75, v83
	v_sub_f32_e32 v124, v74, v82
	ds_read_b128 v[80:83], v163 offset:32768
	s_waitcnt vmcnt(1)
	ds_read_b128 v[96:99], v152
	s_waitcnt lgkmcnt(0)
	s_setprio 3
	v_mfma_f32_32x32x16_bf16 v[80:95], v[80:83], v[96:99], 0
	s_waitcnt vmcnt(0)
	ds_read_b128 v[100:103], v164 offset:32768
	ds_read_b128 v[104:107], v152 offset:1024
	s_waitcnt lgkmcnt(0)
	v_mfma_f32_32x32x16_bf16 v[80:95], v[100:103], v[104:107], v[80:95]
	ds_read_b128 v[100:103], v162 offset:352
	s_waitcnt lgkmcnt(0)
	v_sub_f32_e32 v123, v77, v101
	v_sub_f32_e32 v122, v76, v100
	v_sub_f32_e32 v121, v79, v103
	v_sub_f32_e32 v120, v78, v102
	ds_read_b128 v[100:103], v165 offset:32768
	ds_read_b128 v[108:111], v152 offset:2048
	s_waitcnt lgkmcnt(0)
	v_mfma_f32_32x32x16_bf16 v[80:95], v[100:103], v[108:111], v[80:95]
	ds_read_b128 v[100:103], v162 offset:256
	s_waitcnt lgkmcnt(0)
	v_sub_f32_e32 v135, v67, v103
	v_sub_f32_e32 v134, v66, v102
	v_sub_f32_e32 v137, v65, v101
	v_sub_f32_e32 v136, v64, v100
	ds_read_b128 v[100:103], v166 offset:32768
	ds_read_b128 v[178:181], v152 offset:3072
	s_waitcnt lgkmcnt(0)
	v_mfma_f32_32x32x16_bf16 v[80:95], v[100:103], v[178:181], v[80:95]
	ds_read_b128 v[100:103], v163 offset:32896
	ds_read_b128 v[182:185], v152 offset:4096
	s_waitcnt lgkmcnt(0)
	v_mfma_f32_32x32x16_bf16 v[80:95], v[100:103], v[182:185], v[80:95]
	ds_read_b128 v[100:103], v164 offset:32896
	ds_read_b128 v[186:189], v152 offset:5120
	s_waitcnt lgkmcnt(0)
	v_mfma_f32_32x32x16_bf16 v[80:95], v[100:103], v[186:189], v[80:95]
	ds_read_b128 v[100:103], v165 offset:32896
	ds_read_b128 v[190:193], v152 offset:6144
	s_waitcnt lgkmcnt(0)
	v_mfma_f32_32x32x16_bf16 v[80:95], v[100:103], v[190:193], v[80:95]
	ds_read_b128 v[100:103], v166 offset:32896
	ds_read_b128 v[194:197], v152 offset:7168
	s_waitcnt lgkmcnt(0)
	v_mfma_f32_32x32x16_bf16 v[80:95], v[100:103], v[194:197], v[80:95]
	s_nop 11
	v_pk_add_f32 v[136:137], v[80:81], v[136:137]
	v_pk_add_f32 v[134:135], v[82:83], v[134:135]
	ds_read_b128 v[80:83], v163 offset:40960
	v_pk_add_f32 v[120:121], v[94:95], v[120:121]
	v_pk_add_f32 v[122:123], v[92:93], v[122:123]
	v_pk_add_f32 v[124:125], v[90:91], v[124:125]
	v_pk_add_f32 v[126:127], v[88:89], v[126:127]
	v_pk_add_f32 v[130:131], v[86:87], v[130:131]
	v_pk_add_f32 v[132:133], v[84:85], v[132:133]
	s_waitcnt lgkmcnt(0)
	v_mfma_f32_32x32x16_bf16 v[80:95], v[80:83], v[96:99], 0
	ds_read_b128 v[96:99], v164 offset:40960
	s_waitcnt lgkmcnt(0)
	v_mfma_f32_32x32x16_bf16 v[80:95], v[96:99], v[104:107], v[80:95]
	ds_read_b128 v[96:99], v165 offset:40960
	s_waitcnt lgkmcnt(0)
	v_mfma_f32_32x32x16_bf16 v[80:95], v[96:99], v[108:111], v[80:95]
	ds_read_b128 v[96:99], v166 offset:40960
	s_waitcnt lgkmcnt(0)
	v_mfma_f32_32x32x16_bf16 v[80:95], v[96:99], v[178:181], v[80:95]
	ds_read_b128 v[96:99], v163 offset:41088
	s_waitcnt lgkmcnt(0)
	v_mfma_f32_32x32x16_bf16 v[80:95], v[96:99], v[182:185], v[80:95]
	ds_read_b128 v[96:99], v164 offset:41088
	s_waitcnt lgkmcnt(0)
	v_mfma_f32_32x32x16_bf16 v[80:95], v[96:99], v[186:189], v[80:95]
	ds_read_b128 v[96:99], v165 offset:41088
	s_waitcnt lgkmcnt(0)
	v_mfma_f32_32x32x16_bf16 v[80:95], v[96:99], v[190:193], v[80:95]
	ds_read_b128 v[96:99], v166 offset:41088
	s_waitcnt lgkmcnt(0)
	v_mfma_f32_32x32x16_bf16 v[80:95], v[96:99], v[194:197], v[80:95]
	s_setprio 0
	ds_read_b128 v[96:99], v162 offset:416
	s_waitcnt lgkmcnt(0)
	v_sub_f32_e32 v101, v69, v97
	v_sub_f32_e32 v100, v68, v96
	v_sub_f32_e32 v103, v71, v99
	v_sub_f32_e32 v102, v70, v98
	ds_read_b128 v[96:99], v162 offset:448
	s_nop 4
	v_pk_add_f32 v[84:85], v[84:85], v[100:101]
	v_pk_add_f32 v[86:87], v[86:87], v[102:103]
	s_waitcnt lgkmcnt(0)
	v_sub_f32_e32 v105, v73, v97
	v_sub_f32_e32 v104, v72, v96
	v_sub_f32_e32 v107, v75, v99
	v_sub_f32_e32 v106, v74, v98
	ds_read_b128 v[96:99], v162 offset:480
	v_pk_add_f32 v[90:91], v[90:91], v[106:107]
	v_pk_add_f32 v[88:89], v[88:89], v[104:105]
	s_waitcnt lgkmcnt(0)
	v_sub_f32_e32 v109, v77, v97
	v_sub_f32_e32 v108, v76, v96
	v_sub_f32_e32 v111, v79, v99
	v_sub_f32_e32 v110, v78, v98
	ds_read_b128 v[96:99], v162 offset:384
	v_pk_add_f32 v[92:93], v[92:93], v[108:109]
	s_waitcnt lgkmcnt(0)
	v_sub_f32_e32 v97, v65, v97
	v_sub_f32_e32 v96, v64, v96
	v_pk_add_f32 v[138:139], v[80:81], v[96:97]
	v_pk_add_f32 v[80:81], v[94:95], v[110:111]
	v_lshl_add_u64 v[94:95], v[118:119], 0, v[112:113]
	v_add_co_u32_e32 v96, vcc, 0x11401000, v94
	v_sub_f32_e32 v99, v67, v99
	v_sub_f32_e32 v98, v66, v98
	v_addc_co_u32_e32 v97, vcc, 0, v95, vcc
	v_pk_add_f32 v[82:83], v[82:83], v[98:99]
	v_add_co_u32_e32 v98, vcc, 0x11481000, v94
	s_nop 1
	v_addc_co_u32_e32 v99, vcc, 0, v95, vcc
	v_add_co_u32_e32 v100, vcc, 0x11402000, v94
	s_nop 1
	v_addc_co_u32_e32 v101, vcc, 0, v95, vcc
	v_add_co_u32_e32 v94, vcc, 0x11482000, v94
	s_nop 1
	v_addc_co_u32_e32 v95, vcc, 0, v95, vcc
	global_load_dwordx4 v[108:111], v[96:97], off
	global_load_dwordx4 v[104:107], v[98:99], off
	s_nop 0
	global_load_dwordx4 v[96:99], v[100:101], off
	s_nop 0
	global_load_dwordx4 v[100:103], v[94:95], off
	s_cbranch_scc1 .LBB0_1337
; template <int BUF>
; __device__ __forceinline__ void fox_tile(f32x16* o, float& m_reg, float& l_reg, const char* lds, const float* ckl, float* al_l, int vb0, const bf16x8* qr, float cq, int qpos, int kb0, bool need_mask, int r32, int hi) {
;     ...
;     if (need_mask) { const float NEG = -__builtin_inff(); const int dq = qpos - kb0 - 4 * hi;
; #pragma unroll
;         for (int r = 0; r < 16; ++r) { const int c = (r & 3) + 8 * (r >> 2); if (c > dq) p0[r] = NEG; if (c + 32 > dq) p1[r] = NEG; } }
	v_cmp_gt_i32_e64 s[68:69], 26, v161
	v_cmp_gt_i32_e64 s[70:71], 27, v161
	v_cmp_gt_i32_e64 s[66:67], 25, v161
	s_and_b64 s[68:69], s[70:71], s[68:69]
	v_cmp_gt_i32_e64 s[64:65], 24, v161
	s_and_b64 s[66:67], s[68:69], s[66:67]
	v_cmp_gt_i32_e64 s[62:63], 19, v161
	s_and_b64 s[64:65], s[66:67], s[64:65]
	v_cmp_gt_i32_e64 s[60:61], 18, v161
	s_and_b64 s[62:63], s[64:65], s[62:63]
	v_cmp_gt_i32_e64 s[58:59], 17, v161
	s_and_b64 s[60:61], s[62:63], s[60:61]
	v_cmp_gt_i32_e64 s[56:57], 16, v161
	s_and_b64 s[58:59], s[60:61], s[58:59]
	v_cmp_gt_i32_e64 s[54:55], 11, v161
	s_and_b64 s[56:57], s[58:59], s[56:57]
	v_cmp_gt_i32_e64 s[52:53], 10, v161
	s_and_b64 s[54:55], s[56:57], s[54:55]
	v_cmp_gt_i32_e64 s[50:51], 9, v161
	s_and_b64 s[52:53], s[54:55], s[52:53]
	v_cmp_gt_i32_e64 s[48:49], 8, v161
	s_and_b64 s[50:51], s[52:53], s[50:51]
	v_cmp_gt_i32_e64 s[46:47], 3, v161
	s_and_b64 s[48:49], s[50:51], s[48:49]
	v_cmp_gt_i32_e64 s[44:45], 2, v161
	s_and_b64 s[46:47], s[48:49], s[46:47]
	v_cmp_gt_i32_e64 s[42:43], 1, v161
	s_and_b64 s[44:45], s[46:47], s[44:45]
	v_cmp_gt_i32_e64 s[0:1], 0, v161
	s_and_b64 s[42:43], s[44:45], s[42:43]
	s_and_b64 s[0:1], s[42:43], s[0:1]
	v_cmp_gt_i32_e64 s[38:39], 58, v161
	v_cndmask_b32_e64 v136, v136, v143, s[0:1]
	v_cmp_gt_i32_e64 s[0:1], 59, v161
	v_cmp_gt_i32_e64 s[36:37], 57, v161
	v_cmp_gt_i32_e64 s[34:35], 56, v161
	v_cndmask_b32_e64 v81, v81, v143, s[0:1]
	s_and_b64 s[0:1], s[0:1], s[38:39]
	v_cndmask_b32_e64 v80, v80, v143, s[0:1]
	s_and_b64 s[0:1], s[0:1], s[36:37]
	v_cmp_gt_i32_e64 s[30:31], 51, v161
	v_cndmask_b32_e64 v93, v93, v143, s[0:1]
	s_and_b64 s[0:1], s[0:1], s[34:35]
	v_cmp_gt_i32_e64 s[28:29], 50, v161
	v_cndmask_b32_e64 v92, v92, v143, s[0:1]
	s_and_b64 s[0:1], s[0:1], s[30:31]
	v_cmp_gt_i32_e64 s[26:27], 49, v161
	v_cndmask_b32_e64 v91, v91, v143, s[0:1]
	s_and_b64 s[0:1], s[0:1], s[28:29]
	v_cmp_gt_i32_e64 s[24:25], 48, v161
	v_cndmask_b32_e64 v90, v90, v143, s[0:1]
	s_and_b64 s[0:1], s[0:1], s[26:27]
	v_cmp_gt_i32_e64 s[22:23], 43, v161
	v_cndmask_b32_e64 v89, v89, v143, s[0:1]
	s_and_b64 s[0:1], s[0:1], s[24:25]
	v_cmp_gt_i32_e64 s[20:21], 42, v161
	v_cndmask_b32_e64 v88, v88, v143, s[0:1]
	s_and_b64 s[0:1], s[0:1], s[22:23]
	v_cmp_gt_i32_e64 s[18:19], 41, v161
	v_cndmask_b32_e64 v87, v87, v143, s[0:1]
	s_and_b64 s[0:1], s[0:1], s[20:21]
	v_cmp_gt_i32_e64 s[16:17], 40, v161
	v_cndmask_b32_e64 v86, v86, v143, s[0:1]
	s_and_b64 s[0:1], s[0:1], s[18:19]
	v_cmp_gt_i32_e64 s[14:15], 35, v161
	v_cndmask_b32_e64 v85, v85, v143, s[0:1]
	s_and_b64 s[0:1], s[0:1], s[16:17]
	v_cmp_gt_i32_e64 s[12:13], 34, v161
	v_cndmask_b32_e64 v84, v84, v143, s[0:1]
	s_and_b64 s[0:1], s[0:1], s[14:15]
	v_cmp_gt_i32_e64 s[10:11], 33, v161
	v_cndmask_b32_e64 v83, v83, v143, s[0:1]
	s_and_b64 s[0:1], s[0:1], s[12:13]
	v_cmp_gt_i32_e32 vcc, 32, v161
	v_cndmask_b32_e64 v82, v82, v143, s[0:1]
	s_and_b64 s[0:1], s[0:1], s[10:11]
	s_and_b64 vcc, s[0:1], vcc
	v_cndmask_b32_e64 v121, v121, v143, s[70:71]
	v_cndmask_b32_e64 v120, v120, v143, s[68:69]
	v_cndmask_b32_e64 v123, v123, v143, s[66:67]
	v_cndmask_b32_e64 v122, v122, v143, s[64:65]
	v_cndmask_b32_e64 v125, v125, v143, s[62:63]
	v_cndmask_b32_e64 v124, v124, v143, s[60:61]
	v_cndmask_b32_e64 v127, v127, v143, s[58:59]
	v_cndmask_b32_e64 v126, v126, v143, s[56:57]
	v_cndmask_b32_e64 v131, v131, v143, s[54:55]
	v_cndmask_b32_e64 v130, v130, v143, s[52:53]
	v_cndmask_b32_e64 v133, v133, v143, s[50:51]
	v_cndmask_b32_e64 v132, v132, v143, s[48:49]
	v_cndmask_b32_e64 v135, v135, v143, s[46:47]
	v_cndmask_b32_e64 v134, v134, v143, s[44:45]
	v_cndmask_b32_e64 v137, v137, v143, s[42:43]
	v_cndmask_b32_e64 v139, v139, v143, s[0:1]
	v_cndmask_b32_e32 v138, v138, v143, vcc

; __device__ __forceinline__ unsigned cvtpk(float lo, float hi) { f32x2_t v = {lo, hi}; bf16x2_t b = __builtin_convertvector(v, bf16x2_t); return __builtin_bit_cast(unsigned, b); }
; #define PV_WAIT(n) do { asm volatile("s_waitcnt lgkmcnt(%0)" :: "i"(n) : "memory"); SBAR(); } while (0)
; template <int VB>
; __device__ __forceinline__ void pv_tile(f32x16* o, int vb0, bf16x8 pa0, bf16x8 pa1, bf16x8 pa2, bf16x8 pa3) {
;     ...
;     s16x4 Al0, Al1, Al2, Al3, Ah0, Ah1, Ah2, Ah3, Bl0, Bl1, Bl2, Bl3, Bh0, Bh1, Bh2, Bh3;
;     PV_RD(A, 0); PV_RD(B, 1); PV_WAIT(8); PV_MM(A, 0);
;     PV_RD(A, 2); PV_WAIT(8); PV_MM(B, 1);
;     PV_RD(B, 3); PV_WAIT(8); PV_MM(A, 2);
;     PV_WAIT(0); PV_MM(B, 3);
;     ...
; }
; __device__ __forceinline__ bf16x8 knorm8(bf16x8 x, const float* g) {
;     const v4u xv = __builtin_bit_cast(v4u, x); float f[8];
; #pragma unroll
;     for (int e = 0; e < 4; ++e) { f[2 * e] = __builtin_bit_cast(float, xv[e] << 16); f[2 * e + 1] = __builtin_bit_cast(float, xv[e] & 0xffff0000u); }
;     float s = 0.f;
; #pragma unroll
;     for (int e = 0; e < 8; ++e) s += f[e] * f[e];
;     s += __shfl_xor(s, 1); s += __shfl_xor(s, 2); s += __shfl_xor(s, 4); s += __shfl_xor(s, 8);
;     const float r = __builtin_amdgcn_rsqf(s * (1.0f / 128.0f) + 1e-6f);
;     const f32x4 g0 = *(const f32x4*)g, g1 = *(const f32x4*)(g + 4);
;     v4u w; w.x = cvtpk(f[0] * r * g0[0], f[1] * r * g0[1]); w.y = cvtpk(f[2] * r * g0[2], f[3] * r * g0[3]); w.z = cvtpk(f[4] * r * g1[0], f[5] * r * g1[1]); w.w = cvtpk(f[6] * r * g1[2], f[7] * r * g1[3]);
;     return __builtin_bit_cast(bf16x8, w);
; __device__ __forceinline__ void fox_attn_unit(const Params& P, char* lds, int b, int h, int qb) {
;     ...
;     float m_reg = -1e30f, l_reg = 0.f; f32x16 o[4] = {};
;     __syncthreads();
;     int j_lo; { const float thr = *(const float*)(ws + WS_THR), cq0 = ckl[q0];
;         const bool skip = lane < 4 * qb && ckl[64 * lane + 63] - cq0 > thr; const unsigned long long bm = __ballot(!skip); j_lo = (int)__builtin_ctzll(bm) & ~1; }
;     SLOAD(NT - 1); SWRITE(0);
;     __syncthreads();
;     for (int t = NT - 1; t > j_lo; t -= 2) {
;         SLOAD(t - 1);
;         { const int kb0 = t * 64; fox_tile<0>(o, m_reg, l_reg, lds, ckl, al_l, vb0, qr, cq, qpos, kb0, kb0 + 63 > qlo, r32, hi); }
;         SWRITE(1);
;         __syncthreads();
.LBB0_1341:
	ds_read_b64_tr_b16 v[120:121], v159 offset:0
	ds_read_b64_tr_b16 v[122:123], v159 offset:0x800
	ds_read_b64_tr_b16 v[124:125], v159 offset:0x1000
	ds_read_b64_tr_b16 v[126:127], v159 offset:0x1800
	ds_read_b64_tr_b16 v[130:131], v159 offset:0x2000
	ds_read_b64_tr_b16 v[132:133], v159 offset:0x2800
	ds_read_b64_tr_b16 v[134:135], v159 offset:0x3000
	ds_read_b64_tr_b16 v[136:137], v159 offset:0x3800
	ds_read_b64_tr_b16 v[178:179], v159 offset:0x200
	ds_read_b64_tr_b16 v[180:181], v159 offset:0xa00
	ds_read_b64_tr_b16 v[182:183], v159 offset:0x1200
	ds_read_b64_tr_b16 v[184:185], v159 offset:0x1a00
	ds_read_b64_tr_b16 v[186:187], v159 offset:0x2200
	ds_read_b64_tr_b16 v[188:189], v159 offset:0x2a00
	ds_read_b64_tr_b16 v[190:191], v159 offset:0x3200
	ds_read_b64_tr_b16 v[192:193], v159 offset:0x3a00
	s_waitcnt lgkmcnt(8)
	s_nop 0
	s_setprio 3
	v_mfma_f32_32x32x16_bf16 v[0:15], v[80:83], v[120:123], v[0:15]
	ds_read_b64_tr_b16 v[120:121], v159 offset:0x400
	ds_read_b64_tr_b16 v[122:123], v159 offset:0xc00
	v_mfma_f32_32x32x16_bf16 v[0:15], v[84:87], v[124:127], v[0:15]
	ds_read_b64_tr_b16 v[124:125], v159 offset:0x1400
	ds_read_b64_tr_b16 v[126:127], v159 offset:0x1c00
	v_mfma_f32_32x32x16_bf16 v[0:15], v[88:91], v[130:133], v[0:15]
	ds_read_b64_tr_b16 v[130:131], v159 offset:0x2400
	ds_read_b64_tr_b16 v[132:133], v159 offset:0x2c00
	v_mfma_f32_32x32x16_bf16 v[0:15], v[92:95], v[134:137], v[0:15]
	ds_read_b64_tr_b16 v[134:135], v159 offset:0x3400
	ds_read_b64_tr_b16 v[136:137], v159 offset:0x3c00
	s_waitcnt lgkmcnt(8)
	v_mfma_f32_32x32x16_bf16 v[32:47], v[80:83], v[178:181], v[32:47]
	ds_read_b64_tr_b16 v[178:179], v159 offset:0x600
	ds_read_b64_tr_b16 v[180:181], v159 offset:0xe00
	v_mfma_f32_32x32x16_bf16 v[32:47], v[84:87], v[182:185], v[32:47]
	ds_read_b64_tr_b16 v[182:183], v159 offset:0x1600
	ds_read_b64_tr_b16 v[184:185], v159 offset:0x1e00
	v_mfma_f32_32x32x16_bf16 v[32:47], v[88:91], v[186:189], v[32:47]
	ds_read_b64_tr_b16 v[186:187], v159 offset:0x2600
	ds_read_b64_tr_b16 v[188:189], v159 offset:0x2e00
	v_mfma_f32_32x32x16_bf16 v[32:47], v[92:95], v[190:193], v[32:47]
	ds_read_b64_tr_b16 v[190:191], v159 offset:0x3600
	ds_read_b64_tr_b16 v[192:193], v159 offset:0x3e00
	s_waitcnt lgkmcnt(8)
	v_mfma_f32_32x32x16_bf16 v[48:63], v[80:83], v[120:123], v[48:63]
	s_waitcnt lgkmcnt(0)
	v_mfma_f32_32x32x16_bf16 v[48:63], v[84:87], v[124:127], v[48:63]
	v_mfma_f32_32x32x16_bf16 v[48:63], v[88:91], v[130:133], v[48:63]
	v_mfma_f32_32x32x16_bf16 v[48:63], v[92:95], v[134:137], v[48:63]
	v_mfma_f32_32x32x16_bf16 v[16:31], v[80:83], v[178:181], v[16:31]
	s_waitcnt vmcnt(3)
	v_lshlrev_b32_e32 v124, 16, v108
	v_and_b32_e32 v125, 0xffff0000, v108
	v_lshlrev_b32_e32 v120, 16, v109
	v_and_b32_e32 v121, 0xffff0000, v109
	v_pk_mul_f32 v[126:127], v[124:125], v[124:125]
	v_pk_mul_f32 v[122:123], v[120:121], v[120:121]
	v_add_f32_e32 v126, v126, v127
	v_mfma_f32_32x32x16_bf16 v[16:31], v[84:87], v[182:185], v[16:31]
	v_add_f32_e32 v122, v122, v126
	v_add_f32_e32 v122, v123, v122
	ds_read_b128 v[80:83], v153
	ds_read_b128 v[84:87], v153 offset:16
	s_cmp_gt_i32 s6, s73
	s_cselect_b64 s[78:79], -1, 0
	s_cmp_le_i32 s6, s73
	s_cselect_b64 s[76:77], -1, 0
	v_mfma_f32_32x32x16_bf16 v[16:31], v[88:91], v[186:189], v[16:31]
	v_lshlrev_b32_e32 v88, 16, v111
	v_and_b32_e32 v89, 0xffff0000, v111
	v_mul_f32_e64 v90, v88, v88
	v_mul_f32_e64 v91, v89, v89
	s_and_b64 vcc, exec, s[76:77]
	v_mfma_f32_32x32x16_bf16 v[16:31], v[92:95], v[190:193], v[16:31]
	s_setprio 0
	v_lshlrev_b32_e32 v92, 16, v110
	v_and_b32_e32 v93, 0xffff0000, v110
	v_mul_f32_e64 v94, v92, v92
	v_mul_f32_e64 v95, v93, v93
	v_add_f32_e32 v94, v94, v122
	v_add_f32_e32 v94, v95, v94
	v_add_f32_e32 v90, v90, v94
	v_add_f32_e32 v90, v91, v90
	ds_bpermute_b32 v91, v144, v90
	s_waitcnt lgkmcnt(0)
	v_add_f32_e32 v90, v90, v91
	ds_bpermute_b32 v91, v145, v90
	s_waitcnt lgkmcnt(0)
	v_add_f32_e32 v90, v90, v91
	ds_bpermute_b32 v91, v146, v90
	s_waitcnt lgkmcnt(0)
	v_add_f32_e32 v90, v90, v91
	ds_bpermute_b32 v91, v147, v90
	s_waitcnt lgkmcnt(0)
	v_add_f32_e32 v90, v90, v91
	v_fmamk_f32 v90, v90, 0x3c000000, v141
	v_rsq_f32_e32 v90, v90
	s_nop 0
	v_pk_mul_f32 v[94:95], v[90:91], v[124:125] op_sel_hi:[0,1]
	s_waitcnt vmcnt(2)
	v_lshlrev_b32_e32 v124, 16, v104
	v_and_b32_e32 v125, 0xffff0000, v104
	v_pk_mul_f32 v[80:81], v[80:81], v[94:95]
	v_pk_mul_f32 v[94:95], v[90:91], v[120:121] op_sel_hi:[0,1]
	v_lshlrev_b32_e32 v120, 16, v105
	v_and_b32_e32 v121, 0xffff0000, v105
	v_pk_mul_f32 v[126:127], v[124:125], v[124:125]
	v_pk_mul_f32 v[82:83], v[82:83], v[94:95]
	v_pk_mul_f32 v[122:123], v[120:121], v[120:121]
	v_add_f32_e32 v126, v126, v127
	v_cvt_pk_bf16_f32 v80, v80, v81
	v_cvt_pk_bf16_f32 v81, v82, v83
	v_pk_mul_f32 v[82:83], v[90:91], v[92:93] op_sel_hi:[0,1]
	v_lshlrev_b32_e32 v92, 16, v106
	v_and_b32_e32 v93, 0xffff0000, v106
	v_add_f32_e32 v122, v122, v126
	v_pk_mul_f32 v[94:95], v[92:93], v[92:93]
	v_add_f32_e32 v122, v123, v122
	v_pk_mul_f32 v[82:83], v[84:85], v[82:83]
	v_pk_mul_f32 v[84:85], v[90:91], v[88:89] op_sel_hi:[0,1]
	v_lshlrev_b32_e32 v88, 16, v107
	v_and_b32_e32 v89, 0xffff0000, v107
	v_add_f32_e32 v94, v94, v122
	v_pk_mul_f32 v[90:91], v[88:89], v[88:89]
	v_add_f32_e32 v94, v95, v94
	v_add_f32_e32 v90, v90, v94
	v_add_f32_e32 v90, v91, v90
	ds_bpermute_b32 v91, v144, v90
	v_pk_mul_f32 v[84:85], v[86:87], v[84:85]
	v_cvt_pk_bf16_f32 v82, v82, v83
	v_cvt_pk_bf16_f32 v83, v84, v85
	ds_write_b128 v154, v[80:83] offset:49152
	s_waitcnt lgkmcnt(1)
	v_add_f32_e32 v90, v90, v91
	ds_bpermute_b32 v91, v145, v90
	ds_read_b128 v[80:83], v153
	ds_read_b128 v[84:87], v153 offset:16
	s_waitcnt lgkmcnt(2)
	v_add_f32_e32 v90, v90, v91
	ds_bpermute_b32 v91, v146, v90
	s_waitcnt lgkmcnt(0)
	v_add_f32_e32 v90, v90, v91
	ds_bpermute_b32 v91, v147, v90
	s_waitcnt lgkmcnt(0)
	v_add_f32_e32 v90, v90, v91
	v_fmamk_f32 v90, v90, 0x3c000000, v141
	v_rsq_f32_e32 v90, v90
	s_nop 0
	v_pk_mul_f32 v[94:95], v[90:91], v[124:125] op_sel_hi:[0,1]
	v_pk_mul_f32 v[80:81], v[80:81], v[94:95]
	v_pk_mul_f32 v[94:95], v[90:91], v[120:121] op_sel_hi:[0,1]
	v_pk_mul_f32 v[82:83], v[82:83], v[94:95]
	v_cvt_pk_bf16_f32 v80, v80, v81
	v_cvt_pk_bf16_f32 v81, v82, v83
	v_pk_mul_f32 v[82:83], v[90:91], v[92:93] op_sel_hi:[0,1]
	v_pk_mul_f32 v[82:83], v[84:85], v[82:83]
	v_pk_mul_f32 v[84:85], v[90:91], v[88:89] op_sel_hi:[0,1]
	v_pk_mul_f32 v[84:85], v[86:87], v[84:85]
	v_cvt_pk_bf16_f32 v82, v82, v83
	v_cvt_pk_bf16_f32 v83, v84, v85
	ds_write_b128 v154, v[80:83] offset:57344
	s_waitcnt vmcnt(1)
	ds_write_b128 v157, v[96:99] offset:16384
	s_waitcnt vmcnt(0)
	ds_write_b128 v158, v[100:103] offset:16384
	s_waitcnt lgkmcnt(0)
	s_barrier
; template <int KB>
; __device__ __forceinline__ void qkt(f32x16& p0, f32x16& p1, const char* K_lds, int r32, int hi, const bf16x8* qs) {
;     p0 = f32x16{}; p1 = f32x16{};
;     const char* kb[4];
; #pragma unroll
;     for (int dd = 0; dd < 4; ++dd) kb[dd] = K_lds + KB * SHM_K + KSWZ(r32, (dd * 16 + hi * 8) * 2);
; #pragma unroll
;     for (int d0 = 0; d0 < 8; ++d0) { const char* a = kb[d0 & 3] + (d0 >> 2) * 128;
;         bf16x8 b0 = *reinterpret_cast<const bf16x8*>(a);
;         bf16x8 b1 = *reinterpret_cast<const bf16x8*>(a + 32 * 256);
;         const bf16x8 qf = qs[d0 * 64];
;         p0 = __builtin_amdgcn_mfma_f32_32x32x16_bf16(b0, qf, p0, 0, 0, 0);
;         p1 = __builtin_amdgcn_mfma_f32_32x32x16_bf16(b1, qf, p1, 0, 0, 0); }
; }
; template <int VB>
; __device__ __forceinline__ void pv_tile(f32x16* o, int vb0, bf16x8 pa0, bf16x8 pa1, bf16x8 pa2, bf16x8 pa3) {
;     ...
;     s16x4 Al0, Al1, Al2, Al3, Ah0, Ah1, Ah2, Ah3, Bl0, Bl1, Bl2, Bl3, Bh0, Bh1, Bh2, Bh3;
;     PV_RD(A, 0); PV_RD(B, 1); PV_WAIT(8); PV_MM(A, 0);
;     PV_RD(A, 2); PV_WAIT(8); PV_MM(B, 1);
;     PV_RD(B, 3); PV_WAIT(8); PV_MM(A, 2);
;     PV_WAIT(0); PV_MM(B, 3);
;     ...
; }
; __device__ __forceinline__ bf16x8 knorm8(bf16x8 x, const float* g) {
;     const v4u xv = __builtin_bit_cast(v4u, x); float f[8];
; #pragma unroll
;     for (int e = 0; e < 4; ++e) { f[2 * e] = __builtin_bit_cast(float, xv[e] << 16); f[2 * e + 1] = __builtin_bit_cast(float, xv[e] & 0xffff0000u); }
;     float s = 0.f;
; #pragma unroll
;     for (int e = 0; e < 8; ++e) s += f[e] * f[e];
;     s += __shfl_xor(s, 1); s += __shfl_xor(s, 2); s += __shfl_xor(s, 4); s += __shfl_xor(s, 8);
;     const float r = __builtin_amdgcn_rsqf(s * (1.0f / 128.0f) + 1e-6f);
;     const f32x4 g0 = *(const f32x4*)g, g1 = *(const f32x4*)(g + 4);
;     v4u w; w.x = cvtpk(f[0] * r * g0[0], f[1] * r * g0[1]); w.y = cvtpk(f[2] * r * g0[2], f[3] * r * g0[3]); w.z = cvtpk(f[4] * r * g1[0], f[5] * r * g1[1]); w.w = cvtpk(f[6] * r * g1[2], f[7] * r * g1[3]);
;     return __builtin_bit_cast(bf16x8, w);
; }
; template <int BUF>
; __device__ __forceinline__ void fox_tile(f32x16* o, float& m_reg, float& l_reg, const char* lds, const float* ckl, float* al_l, int vb0, const bf16x8* qr, float cq, int qpos, int kb0, bool need_mask, int r32, int hi) {
;     f32x16 p0, p1;
;     qkt<BUF>(p0, p1, lds + 2 * SHM_V, r32, hi, qr);
	s_cbranch_vccnz .LBB0_1343
	v_lshl_add_u64 v[80:81], v[116:117], 0, v[112:113]
	v_add_co_u32_e32 v82, vcc, 0x11401000, v80
	s_nop 1
	v_addc_co_u32_e32 v83, vcc, 0, v81, vcc
	v_add_co_u32_e32 v84, vcc, 0x11481000, v80
	s_nop 1
	v_addc_co_u32_e32 v85, vcc, 0, v81, vcc
	global_load_dwordx4 v[108:111], v[82:83], off
	global_load_dwordx4 v[104:107], v[84:85], off
	v_add_co_u32_e32 v82, vcc, 0x11402000, v80
	s_nop 1
	v_addc_co_u32_e32 v83, vcc, 0, v81, vcc
	v_add_co_u32_e32 v80, vcc, 0x11482000, v80
	s_nop 1
	v_addc_co_u32_e32 v81, vcc, 0, v81, vcc
	global_load_dwordx4 v[96:99], v[82:83], off
	global_load_dwordx4 v[100:103], v[80:81], off
.LBB0_1343:
	ds_read_b128 v[80:83], v162 offset:32
	s_cmp_le_i32 s72, s86
	s_waitcnt lgkmcnt(0)
	v_sub_f32_e32 v133, v69, v81
	v_sub_f32_e32 v132, v68, v80
	v_sub_f32_e32 v131, v71, v83
	v_sub_f32_e32 v130, v70, v82
	ds_read_b128 v[80:83], v162 offset:64
	s_waitcnt lgkmcnt(0)
	v_sub_f32_e32 v127, v73, v81
	v_sub_f32_e32 v126, v72, v80
	v_sub_f32_e32 v125, v75, v83
	v_sub_f32_e32 v124, v74, v82
	ds_read_b128 v[80:83], v163 offset:49152
	ds_read_b128 v[178:181], v152
	s_waitcnt lgkmcnt(0)
	s_setprio 3
	v_mfma_f32_32x32x16_bf16 v[80:95], v[80:83], v[178:181], 0
	ds_read_b128 v[120:123], v164 offset:49152
	ds_read_b128 v[182:185], v152 offset:1024
	s_waitcnt lgkmcnt(0)
	v_mfma_f32_32x32x16_bf16 v[80:95], v[120:123], v[182:185], v[80:95]
	ds_read_b128 v[120:123], v162 offset:96
	s_waitcnt lgkmcnt(0)
	v_sub_f32_e32 v135, v77, v121
	v_sub_f32_e32 v134, v76, v120
	v_sub_f32_e32 v139, v79, v123
	v_sub_f32_e32 v138, v78, v122
	ds_read_b128 v[120:123], v165 offset:49152
	ds_read_b128 v[186:189], v152 offset:2048
	s_waitcnt lgkmcnt(0)
	v_mfma_f32_32x32x16_bf16 v[80:95], v[120:123], v[186:189], v[80:95]
	ds_read_b128 v[120:123], v162
	s_waitcnt lgkmcnt(0)
	v_sub_f32_e32 v211, v67, v123
	v_sub_f32_e32 v210, v66, v122
	v_sub_f32_e32 v137, v65, v121
	v_sub_f32_e32 v136, v64, v120
	ds_read_b128 v[120:123], v166 offset:49152
	ds_read_b128 v[190:193], v152 offset:3072
	s_waitcnt lgkmcnt(0)
	v_mfma_f32_32x32x16_bf16 v[80:95], v[120:123], v[190:193], v[80:95]
	ds_read_b128 v[120:123], v163 offset:49280
	ds_read_b128 v[194:197], v152 offset:4096
	s_waitcnt lgkmcnt(0)
	v_mfma_f32_32x32x16_bf16 v[80:95], v[120:123], v[194:197], v[80:95]
	ds_read_b128 v[120:123], v164 offset:49280
	ds_read_b128 v[198:201], v152 offset:5120
	s_waitcnt lgkmcnt(0)
	v_mfma_f32_32x32x16_bf16 v[80:95], v[120:123], v[198:201], v[80:95]
	ds_read_b128 v[120:123], v165 offset:49280
	ds_read_b128 v[202:205], v152 offset:6144
	s_waitcnt lgkmcnt(0)
	v_mfma_f32_32x32x16_bf16 v[80:95], v[120:123], v[202:205], v[80:95]
	ds_read_b128 v[120:123], v166 offset:49280
	ds_read_b128 v[206:209], v152 offset:7168
	s_waitcnt lgkmcnt(0)
	v_mfma_f32_32x32x16_bf16 v[80:95], v[120:123], v[206:209], v[80:95]
	s_nop 11
	v_pk_add_f32 v[136:137], v[80:81], v[136:137]
	v_pk_add_f32 v[122:123], v[92:93], v[134:135]
	v_pk_add_f32 v[134:135], v[82:83], v[210:211]
	ds_read_b128 v[80:83], v163 offset:57344
	v_pk_add_f32 v[120:121], v[94:95], v[138:139]
	v_pk_add_f32 v[124:125], v[90:91], v[124:125]
	v_pk_add_f32 v[126:127], v[88:89], v[126:127]
	v_pk_add_f32 v[130:131], v[86:87], v[130:131]
	v_pk_add_f32 v[132:133], v[84:85], v[132:133]
	s_waitcnt lgkmcnt(0)
	v_mfma_f32_32x32x16_bf16 v[80:95], v[80:83], v[178:181], 0
	ds_read_b128 v[178:181], v164 offset:57344
	s_waitcnt lgkmcnt(0)
	v_mfma_f32_32x32x16_bf16 v[80:95], v[178:181], v[182:185], v[80:95]
	ds_read_b128 v[178:181], v165 offset:57344
	s_waitcnt lgkmcnt(0)
	v_mfma_f32_32x32x16_bf16 v[80:95], v[178:181], v[186:189], v[80:95]
	ds_read_b128 v[178:181], v166 offset:57344
	s_waitcnt lgkmcnt(0)
	v_mfma_f32_32x32x16_bf16 v[80:95], v[178:181], v[190:193], v[80:95]
	ds_read_b128 v[178:181], v163 offset:57472
	s_waitcnt lgkmcnt(0)
	v_mfma_f32_32x32x16_bf16 v[80:95], v[178:181], v[194:197], v[80:95]
	ds_read_b128 v[178:181], v164 offset:57472
	s_waitcnt lgkmcnt(0)
	v_mfma_f32_32x32x16_bf16 v[80:95], v[178:181], v[198:201], v[80:95]
	ds_read_b128 v[178:181], v165 offset:57472
	s_waitcnt lgkmcnt(0)
	v_mfma_f32_32x32x16_bf16 v[80:95], v[178:181], v[202:205], v[80:95]
	ds_read_b128 v[178:181], v166 offset:57472
	s_waitcnt lgkmcnt(0)
	v_mfma_f32_32x32x16_bf16 v[80:95], v[178:181], v[206:209], v[80:95]
	s_setprio 0
	ds_read_b128 v[178:181], v162 offset:160
	s_waitcnt lgkmcnt(0)
	v_sub_f32_e32 v183, v69, v179
	v_sub_f32_e32 v182, v68, v178
	v_sub_f32_e32 v185, v71, v181
	v_sub_f32_e32 v184, v70, v180
	ds_read_b128 v[178:181], v162 offset:192
	s_nop 4
	v_pk_add_f32 v[86:87], v[86:87], v[184:185]
	v_pk_add_f32 v[84:85], v[84:85], v[182:183]
	s_waitcnt lgkmcnt(0)
	v_sub_f32_e32 v187, v73, v179
	v_sub_f32_e32 v186, v72, v178
	v_sub_f32_e32 v189, v75, v181
	v_sub_f32_e32 v188, v74, v180
	ds_read_b128 v[178:181], v162 offset:224
	v_pk_add_f32 v[90:91], v[90:91], v[188:189]
	v_pk_add_f32 v[88:89], v[88:89], v[186:187]
	s_waitcnt lgkmcnt(0)
	v_sub_f32_e32 v191, v77, v179
	v_sub_f32_e32 v190, v76, v178
	v_sub_f32_e32 v193, v79, v181
	v_sub_f32_e32 v192, v78, v180
	ds_read_b128 v[178:181], v162 offset:128
	v_pk_add_f32 v[92:93], v[92:93], v[190:191]
	s_waitcnt lgkmcnt(0)
	v_sub_f32_e32 v181, v67, v181
	v_sub_f32_e32 v180, v66, v180
	v_sub_f32_e32 v139, v65, v179
	v_sub_f32_e32 v138, v64, v178
	v_pk_add_f32 v[138:139], v[80:81], v[138:139]
	v_pk_add_f32 v[80:81], v[94:95], v[192:193]
	v_pk_add_f32 v[82:83], v[82:83], v[180:181]
	s_cbranch_scc1 .LBB0_1345
; template <int BUF>
; __device__ __forceinline__ void fox_tile(f32x16* o, float& m_reg, float& l_reg, const char* lds, const float* ckl, float* al_l, int vb0, const bf16x8* qr, float cq, int qpos, int kb0, bool need_mask, int r32, int hi) {
;     ...
;     if (need_mask) { const float NEG = -__builtin_inff(); const int dq = qpos - kb0 - 4 * hi;
; #pragma unroll
;         for (int r = 0; r < 16; ++r) { const int c = (r & 3) + 8 * (r >> 2); if (c > dq) p0[r] = NEG; if (c + 32 > dq) p1[r] = NEG; } }
	v_add_u32_e32 v94, 64, v161
	v_cmp_gt_i32_e64 s[68:69], 26, v94
	v_cmp_gt_i32_e64 s[70:71], 27, v94
	v_cmp_gt_i32_e64 s[66:67], 25, v94
	s_and_b64 s[68:69], s[70:71], s[68:69]
	v_cmp_gt_i32_e64 s[64:65], 24, v94
	s_and_b64 s[66:67], s[68:69], s[66:67]
	v_cmp_gt_i32_e64 s[62:63], 19, v94
	s_and_b64 s[64:65], s[66:67], s[64:65]
	v_cmp_gt_i32_e64 s[60:61], 18, v94
	s_and_b64 s[62:63], s[64:65], s[62:63]
	v_cmp_gt_i32_e64 s[58:59], 17, v94
	s_and_b64 s[60:61], s[62:63], s[60:61]
	v_cmp_gt_i32_e64 s[56:57], 16, v94
	s_and_b64 s[58:59], s[60:61], s[58:59]
	v_cmp_gt_i32_e64 s[54:55], 11, v94
	s_and_b64 s[56:57], s[58:59], s[56:57]
	v_cmp_gt_i32_e64 s[52:53], 10, v94
	s_and_b64 s[54:55], s[56:57], s[54:55]
	v_cmp_gt_i32_e64 s[50:51], 9, v94
	s_and_b64 s[52:53], s[54:55], s[52:53]
	v_cmp_gt_i32_e64 s[48:49], 8, v94
	s_and_b64 s[50:51], s[52:53], s[50:51]
	v_cmp_gt_i32_e64 s[46:47], 3, v94
	s_and_b64 s[48:49], s[50:51], s[48:49]
	v_cmp_gt_i32_e64 s[44:45], 2, v94
	s_and_b64 s[46:47], s[48:49], s[46:47]
	v_cmp_gt_i32_e64 s[42:43], 1, v94
	s_and_b64 s[44:45], s[46:47], s[44:45]
	v_cmp_gt_i32_e64 s[0:1], 0, v94
	s_and_b64 s[42:43], s[44:45], s[42:43]
	s_and_b64 s[0:1], s[42:43], s[0:1]
	v_cmp_gt_i32_e64 s[38:39], 58, v94
	v_cndmask_b32_e64 v136, v136, v143, s[0:1]
	v_cmp_gt_i32_e64 s[0:1], 59, v94
	v_cmp_gt_i32_e64 s[36:37], 57, v94
	v_cmp_gt_i32_e64 s[34:35], 56, v94
	v_cndmask_b32_e64 v81, v81, v143, s[0:1]
	s_and_b64 s[0:1], s[0:1], s[38:39]
	v_cndmask_b32_e64 v80, v80, v143, s[0:1]
	s_and_b64 s[0:1], s[0:1], s[36:37]
	v_cmp_gt_i32_e64 s[30:31], 51, v94
	v_cndmask_b32_e64 v93, v93, v143, s[0:1]
	s_and_b64 s[0:1], s[0:1], s[34:35]
	v_cmp_gt_i32_e64 s[28:29], 50, v94
	v_cndmask_b32_e64 v92, v92, v143, s[0:1]
	s_and_b64 s[0:1], s[0:1], s[30:31]
	v_cmp_gt_i32_e64 s[26:27], 49, v94
	v_cndmask_b32_e64 v91, v91, v143, s[0:1]
	s_and_b64 s[0:1], s[0:1], s[28:29]
	v_cmp_gt_i32_e64 s[24:25], 48, v94
	v_cndmask_b32_e64 v90, v90, v143, s[0:1]
	s_and_b64 s[0:1], s[0:1], s[26:27]
	v_cmp_gt_i32_e64 s[22:23], 43, v94
	v_cndmask_b32_e64 v89, v89, v143, s[0:1]
	s_and_b64 s[0:1], s[0:1], s[24:25]
	v_cmp_gt_i32_e64 s[20:21], 42, v94
	v_cndmask_b32_e64 v88, v88, v143, s[0:1]
	s_and_b64 s[0:1], s[0:1], s[22:23]
	v_cmp_gt_i32_e64 s[18:19], 41, v94
	v_cndmask_b32_e64 v87, v87, v143, s[0:1]
	s_and_b64 s[0:1], s[0:1], s[20:21]
	v_cmp_gt_i32_e64 s[16:17], 40, v94
	v_cndmask_b32_e64 v86, v86, v143, s[0:1]
	s_and_b64 s[0:1], s[0:1], s[18:19]
	v_cmp_gt_i32_e64 s[14:15], 35, v94
	v_cndmask_b32_e64 v85, v85, v143, s[0:1]
	s_and_b64 s[0:1], s[0:1], s[16:17]
	v_cmp_gt_i32_e64 s[12:13], 34, v94
	v_cndmask_b32_e64 v84, v84, v143, s[0:1]
	s_and_b64 s[0:1], s[0:1], s[14:15]
	v_cmp_gt_i32_e64 s[10:11], 33, v94
	v_cndmask_b32_e64 v83, v83, v143, s[0:1]
	s_and_b64 s[0:1], s[0:1], s[12:13]
	v_cmp_gt_i32_e32 vcc, 32, v94
	v_cndmask_b32_e64 v82, v82, v143, s[0:1]
	s_and_b64 s[0:1], s[0:1], s[10:11]
	s_and_b64 vcc, s[0:1], vcc
	v_cndmask_b32_e64 v121, v121, v143, s[70:71]
	v_cndmask_b32_e64 v120, v120, v143, s[68:69]
	v_cndmask_b32_e64 v123, v123, v143, s[66:67]
	v_cndmask_b32_e64 v122, v122, v143, s[64:65]
	v_cndmask_b32_e64 v125, v125, v143, s[62:63]
	v_cndmask_b32_e64 v124, v124, v143, s[60:61]
	v_cndmask_b32_e64 v127, v127, v143, s[58:59]
	v_cndmask_b32_e64 v126, v126, v143, s[56:57]
	v_cndmask_b32_e64 v131, v131, v143, s[54:55]
	v_cndmask_b32_e64 v130, v130, v143, s[52:53]
	v_cndmask_b32_e64 v133, v133, v143, s[50:51]
	v_cndmask_b32_e64 v132, v132, v143, s[48:49]
	v_cndmask_b32_e64 v135, v135, v143, s[46:47]
	v_cndmask_b32_e64 v134, v134, v143, s[44:45]
	v_cndmask_b32_e64 v137, v137, v143, s[42:43]
	v_cndmask_b32_e64 v139, v139, v143, s[0:1]
	v_cndmask_b32_e32 v138, v138, v143, vcc

; __device__ __forceinline__ unsigned cvtpk(float lo, float hi) { f32x2_t v = {lo, hi}; bf16x2_t b = __builtin_convertvector(v, bf16x2_t); return __builtin_bit_cast(unsigned, b); }
; #define PV_RD(S, d0) do { constexpr int b_ = VB * SHM_V + v_rd_off(d0, 0, 0); \
;         TRRD(S##l0, b_); TRRD(S##h0, b_ + 2048); TRRD(S##l1, b_ + 4096); TRRD(S##h1, b_ + 6144); TRRD(S##l2, b_ + 8192); TRRD(S##h2, b_ + 10240); TRRD(S##l3, b_ + 12288); TRRD(S##h3, b_ + 14336); } while (0)
; #define PV_WAIT(n) do { asm volatile("s_waitcnt lgkmcnt(%0)" :: "i"(n) : "memory"); SBAR(); } while (0)
; #define SWRITE(bf) do { *(bf16x8*)(K_lds + (bf) * SHM_K + kws) = knorm8(st_k0, kgl + sc); *(bf16x8*)(K_lds + (bf) * SHM_K + kws + 32 * 256) = knorm8(st_k1, kgl + sc); \
;         *(bf16x8*)(V_lds + (bf) * SHM_V + vst0) = st_v0; *(bf16x8*)(V_lds + (bf) * SHM_V + vst1) = st_v1; } while (0)
; template <int VB>
; __device__ __forceinline__ void pv_tile(f32x16* o, int vb0, bf16x8 pa0, bf16x8 pa1, bf16x8 pa2, bf16x8 pa3) {
;     ...
;     s16x4 Al0, Al1, Al2, Al3, Ah0, Ah1, Ah2, Ah3, Bl0, Bl1, Bl2, Bl3, Bh0, Bh1, Bh2, Bh3;
;     PV_RD(A, 0); PV_RD(B, 1); PV_WAIT(8); PV_MM(A, 0);
;     PV_RD(A, 2); PV_WAIT(8); PV_MM(B, 1);
;     PV_RD(B, 3); PV_WAIT(8); PV_MM(A, 2);
;     PV_WAIT(0); PV_MM(B, 3);
;     ...
; }
; __device__ __forceinline__ bf16x8 knorm8(bf16x8 x, const float* g) {
;     const v4u xv = __builtin_bit_cast(v4u, x); float f[8];
; #pragma unroll
;     for (int e = 0; e < 4; ++e) { f[2 * e] = __builtin_bit_cast(float, xv[e] << 16); f[2 * e + 1] = __builtin_bit_cast(float, xv[e] & 0xffff0000u); }
;     float s = 0.f;
; #pragma unroll
;     for (int e = 0; e < 8; ++e) s += f[e] * f[e];
;     s += __shfl_xor(s, 1); s += __shfl_xor(s, 2); s += __shfl_xor(s, 4); s += __shfl_xor(s, 8);
;     const float r = __builtin_amdgcn_rsqf(s * (1.0f / 128.0f) + 1e-6f);
;     const f32x4 g0 = *(const f32x4*)g, g1 = *(const f32x4*)(g + 4);
;     v4u w; w.x = cvtpk(f[0] * r * g0[0], f[1] * r * g0[1]); w.y = cvtpk(f[2] * r * g0[2], f[3] * r * g0[3]); w.z = cvtpk(f[4] * r * g1[0], f[5] * r * g1[1]); w.w = cvtpk(f[6] * r * g1[2], f[7] * r * g1[3]);
;     return __builtin_bit_cast(bf16x8, w);
; __device__ __forceinline__ void fox_attn_unit(const Params& P, char* lds, int b, int h, int qb) {
;     ...
;         if (t - 2 > j_lo) SWRITE(0);
;         __syncthreads();
;     }
.LBB0_1349:
	ds_read_b64_tr_b16 v[124:125], v159 offset:0x4000
	ds_read_b64_tr_b16 v[126:127], v159 offset:0x4800
	ds_read_b64_tr_b16 v[130:131], v159 offset:0x5000
	ds_read_b64_tr_b16 v[132:133], v159 offset:0x5800
	ds_read_b64_tr_b16 v[134:135], v159 offset:0x6000
	ds_read_b64_tr_b16 v[136:137], v159 offset:0x6800
	ds_read_b64_tr_b16 v[178:179], v159 offset:0x7000
	ds_read_b64_tr_b16 v[180:181], v159 offset:0x7800
	ds_read_b64_tr_b16 v[182:183], v159 offset:0x4200
	ds_read_b64_tr_b16 v[184:185], v159 offset:0x4a00
	ds_read_b64_tr_b16 v[186:187], v159 offset:0x5200
	ds_read_b64_tr_b16 v[188:189], v159 offset:0x5a00
	ds_read_b64_tr_b16 v[190:191], v159 offset:0x6200
	ds_read_b64_tr_b16 v[192:193], v159 offset:0x6a00
	ds_read_b64_tr_b16 v[194:195], v159 offset:0x7200
	ds_read_b64_tr_b16 v[196:197], v159 offset:0x7a00
	s_waitcnt lgkmcnt(8)
	s_nop 0
	s_setprio 3
	v_mfma_f32_32x32x16_bf16 v[0:15], v[80:83], v[124:127], v[0:15]
	ds_read_b64_tr_b16 v[124:125], v159 offset:0x4400
	ds_read_b64_tr_b16 v[126:127], v159 offset:0x4c00
	v_mfma_f32_32x32x16_bf16 v[0:15], v[84:87], v[130:133], v[0:15]
	ds_read_b64_tr_b16 v[130:131], v159 offset:0x5400
	ds_read_b64_tr_b16 v[132:133], v159 offset:0x5c00
	v_mfma_f32_32x32x16_bf16 v[0:15], v[88:91], v[134:137], v[0:15]
	ds_read_b64_tr_b16 v[134:135], v159 offset:0x6400
	ds_read_b64_tr_b16 v[136:137], v159 offset:0x6c00
	v_mfma_f32_32x32x16_bf16 v[0:15], v[92:95], v[178:181], v[0:15]
	ds_read_b64_tr_b16 v[178:179], v159 offset:0x7400
	ds_read_b64_tr_b16 v[180:181], v159 offset:0x7c00
	s_waitcnt lgkmcnt(8)
	v_mfma_f32_32x32x16_bf16 v[32:47], v[80:83], v[182:185], v[32:47]
	ds_read_b64_tr_b16 v[182:183], v159 offset:0x4600
	ds_read_b64_tr_b16 v[184:185], v159 offset:0x4e00
	v_mfma_f32_32x32x16_bf16 v[32:47], v[84:87], v[186:189], v[32:47]
	ds_read_b64_tr_b16 v[186:187], v159 offset:0x5600
	ds_read_b64_tr_b16 v[188:189], v159 offset:0x5e00
	v_mfma_f32_32x32x16_bf16 v[32:47], v[88:91], v[190:193], v[32:47]
	ds_read_b64_tr_b16 v[190:191], v159 offset:0x6600
	ds_read_b64_tr_b16 v[192:193], v159 offset:0x6e00
	v_mfma_f32_32x32x16_bf16 v[32:47], v[92:95], v[194:197], v[32:47]
	ds_read_b64_tr_b16 v[194:195], v159 offset:0x7600
	ds_read_b64_tr_b16 v[196:197], v159 offset:0x7e00
	s_waitcnt lgkmcnt(8)
	v_mfma_f32_32x32x16_bf16 v[48:63], v[80:83], v[124:127], v[48:63]
	s_waitcnt lgkmcnt(0)
	v_mfma_f32_32x32x16_bf16 v[48:63], v[84:87], v[130:133], v[48:63]
	v_mfma_f32_32x32x16_bf16 v[48:63], v[88:91], v[134:137], v[48:63]
	v_mfma_f32_32x32x16_bf16 v[48:63], v[92:95], v[178:181], v[48:63]
	v_mfma_f32_32x32x16_bf16 v[16:31], v[80:83], v[182:185], v[16:31]
	s_andn2_b64 vcc, exec, s[78:79]
	v_mfma_f32_32x32x16_bf16 v[16:31], v[84:87], v[186:189], v[16:31]
	v_mfma_f32_32x32x16_bf16 v[16:31], v[88:91], v[190:193], v[16:31]
	v_mfma_f32_32x32x16_bf16 v[16:31], v[92:95], v[194:197], v[16:31]
	s_setprio 0
	s_cbranch_vccnz .LBB0_1334
	s_waitcnt vmcnt(3)
	v_lshlrev_b32_e32 v94, 16, v108
	v_and_b32_e32 v95, 0xffff0000, v108
	v_lshlrev_b32_e32 v92, 16, v109
	v_and_b32_e32 v93, 0xffff0000, v109
	v_pk_mul_f32 v[86:87], v[94:95], v[94:95]
	v_pk_mul_f32 v[84:85], v[92:93], v[92:93]
	v_add_f32_e32 v86, v86, v87
	v_lshlrev_b32_e32 v90, 16, v110
	v_and_b32_e32 v91, 0xffff0000, v110
	v_add_f32_e32 v84, v84, v86
	v_pk_mul_f32 v[82:83], v[90:91], v[90:91]
	v_add_f32_e32 v84, v85, v84
	v_lshlrev_b32_e32 v88, 16, v111
	v_and_b32_e32 v89, 0xffff0000, v111
	v_add_f32_e32 v82, v82, v84
	v_pk_mul_f32 v[80:81], v[88:89], v[88:89]
	v_add_f32_e32 v82, v83, v82
	v_add_f32_e32 v80, v80, v82
	v_add_f32_e32 v80, v81, v80
	ds_bpermute_b32 v81, v144, v80
	s_waitcnt vmcnt(2)
	v_lshlrev_b32_e32 v126, 16, v104
	v_and_b32_e32 v127, 0xffff0000, v104
	v_lshlrev_b32_e32 v124, 16, v105
	v_and_b32_e32 v125, 0xffff0000, v105
	s_waitcnt lgkmcnt(0)
	v_add_f32_e32 v80, v80, v81
	ds_bpermute_b32 v81, v145, v80
	v_pk_mul_f32 v[86:87], v[126:127], v[126:127]
	v_lshlrev_b32_e32 v110, 16, v106
	v_and_b32_e32 v111, 0xffff0000, v106
	v_add_f32_e32 v86, v86, v87
	s_waitcnt lgkmcnt(0)
	v_add_f32_e32 v80, v80, v81
	ds_bpermute_b32 v81, v146, v80
	v_pk_mul_f32 v[82:83], v[110:111], v[110:111]
	v_lshlrev_b32_e32 v108, 16, v107
	v_and_b32_e32 v109, 0xffff0000, v107
	s_waitcnt lgkmcnt(0)
	v_add_f32_e32 v84, v80, v81
	ds_bpermute_b32 v85, v147, v84
	v_pk_mul_f32 v[80:81], v[108:109], v[108:109]
	s_waitcnt lgkmcnt(0)
	v_add_f32_e32 v84, v84, v85
	v_fmamk_f32 v84, v84, 0x3c000000, v141
	v_rsq_f32_e32 v106, v84
	v_pk_mul_f32 v[84:85], v[124:125], v[124:125]
	v_pk_mul_f32 v[92:93], v[106:107], v[92:93] op_sel_hi:[0,1]
	v_add_f32_e32 v84, v84, v86
	v_add_f32_e32 v84, v85, v84
	v_add_f32_e32 v82, v82, v84
	v_add_f32_e32 v82, v83, v82
	v_add_f32_e32 v80, v80, v82
	v_add_f32_e32 v104, v81, v80
	ds_bpermute_b32 v105, v144, v104
	ds_read_b128 v[80:83], v153
	ds_read_b128 v[84:87], v153 offset:16
	v_pk_mul_f32 v[94:95], v[106:107], v[94:95] op_sel_hi:[0,1]
	s_waitcnt lgkmcnt(2)
	v_add_f32_e32 v104, v104, v105
	ds_bpermute_b32 v105, v145, v104
	s_waitcnt lgkmcnt(2)
	v_pk_mul_f32 v[82:83], v[82:83], v[92:93]
	v_pk_mul_f32 v[80:81], v[80:81], v[94:95]
	s_waitcnt lgkmcnt(0)
	v_add_f32_e32 v92, v104, v105
	ds_bpermute_b32 v93, v146, v92
	v_cvt_pk_bf16_f32 v80, v80, v81
	v_cvt_pk_bf16_f32 v81, v82, v83
	v_pk_mul_f32 v[82:83], v[106:107], v[90:91] op_sel_hi:[0,1]
	v_pk_mul_f32 v[82:83], v[84:85], v[82:83]
	s_waitcnt lgkmcnt(0)
	v_add_f32_e32 v90, v92, v93
	ds_bpermute_b32 v91, v147, v90
	v_pk_mul_f32 v[84:85], v[106:107], v[88:89] op_sel_hi:[0,1]
	v_pk_mul_f32 v[84:85], v[86:87], v[84:85]
	v_cvt_pk_bf16_f32 v82, v82, v83
	v_cvt_pk_bf16_f32 v83, v84, v85
	ds_write_b128 v154, v[80:83] offset:32768
	s_waitcnt lgkmcnt(1)
	v_add_f32_e32 v80, v90, v91
	v_fmamk_f32 v80, v80, 0x3c000000, v141
	v_rsq_f32_e32 v88, v80
	ds_read_b128 v[80:83], v153
	ds_read_b128 v[84:87], v153 offset:16
	v_pk_mul_f32 v[90:91], v[88:89], v[126:127] op_sel_hi:[0,1]
	s_waitcnt lgkmcnt(1)
	v_pk_mul_f32 v[80:81], v[80:81], v[90:91]
	v_pk_mul_f32 v[90:91], v[88:89], v[124:125] op_sel_hi:[0,1]
	v_pk_mul_f32 v[82:83], v[82:83], v[90:91]
	v_cvt_pk_bf16_f32 v80, v80, v81
	v_cvt_pk_bf16_f32 v81, v82, v83
	v_pk_mul_f32 v[82:83], v[88:89], v[110:111] op_sel_hi:[0,1]
	s_waitcnt lgkmcnt(0)
	v_pk_mul_f32 v[82:83], v[84:85], v[82:83]
	v_pk_mul_f32 v[84:85], v[88:89], v[108:109] op_sel_hi:[0,1]
	v_pk_mul_f32 v[84:85], v[86:87], v[84:85]
	v_cvt_pk_bf16_f32 v82, v82, v83
	v_cvt_pk_bf16_f32 v83, v84, v85
	ds_write_b128 v154, v[80:83] offset:40960
	s_waitcnt vmcnt(1)
	ds_write_b128 v157, v[96:99]
	s_waitcnt vmcnt(0)
	ds_write_b128 v158, v[100:103]
	s_branch .LBB0_1334

; template <int KB>
; __device__ __forceinline__ void qkt(f32x16& p0, f32x16& p1, const char* K_lds, int r32, int hi, const bf16x8* qs) {
;     p0 = f32x16{}; p1 = f32x16{};
;     const char* kb[4];
; #pragma unroll
;     for (int dd = 0; dd < 4; ++dd) kb[dd] = K_lds + KB * SHM_K + KSWZ(r32, (dd * 16 + hi * 8) * 2);
; #pragma unroll
;     for (int d0 = 0; d0 < 8; ++d0) { const char* a = kb[d0 & 3] + (d0 >> 2) * 128;
;         bf16x8 b0 = *reinterpret_cast<const bf16x8*>(a);
;         bf16x8 b1 = *reinterpret_cast<const bf16x8*>(a + 32 * 256);
;         const bf16x8 qf = qs[d0 * 64];
;         p0 = __builtin_amdgcn_mfma_f32_32x32x16_bf16(b0, qf, p0, 0, 0, 0);
;         p1 = __builtin_amdgcn_mfma_f32_32x32x16_bf16(b1, qf, p1, 0, 0, 0); }
; }
; template <int VB>
; __device__ __forceinline__ void pv_tile(f32x16* o, int vb0, bf16x8 pa0, bf16x8 pa1, bf16x8 pa2, bf16x8 pa3) {
;     ...
;     s16x4 Al0, Al1, Al2, Al3, Ah0, Ah1, Ah2, Ah3, Bl0, Bl1, Bl2, Bl3, Bh0, Bh1, Bh2, Bh3;
;     PV_RD(A, 0); PV_RD(B, 1); PV_WAIT(8); PV_MM(A, 0);
;     PV_RD(A, 2); PV_WAIT(8); PV_MM(B, 1);
;     PV_RD(B, 3); PV_WAIT(8); PV_MM(A, 2);
;     PV_WAIT(0); PV_MM(B, 3);
;     ...
; }
; __device__ __forceinline__ bf16x8 knorm8(bf16x8 x, const float* g) {
;     const v4u xv = __builtin_bit_cast(v4u, x); float f[8];
; #pragma unroll
;     for (int e = 0; e < 4; ++e) { f[2 * e] = __builtin_bit_cast(float, xv[e] << 16); f[2 * e + 1] = __builtin_bit_cast(float, xv[e] & 0xffff0000u); }
;     float s = 0.f;
; #pragma unroll
;     for (int e = 0; e < 8; ++e) s += f[e] * f[e];
;     s += __shfl_xor(s, 1); s += __shfl_xor(s, 2); s += __shfl_xor(s, 4); s += __shfl_xor(s, 8);
;     const float r = __builtin_amdgcn_rsqf(s * (1.0f / 128.0f) + 1e-6f);
;     const f32x4 g0 = *(const f32x4*)g, g1 = *(const f32x4*)(g + 4);
;     v4u w; w.x = cvtpk(f[0] * r * g0[0], f[1] * r * g0[1]); w.y = cvtpk(f[2] * r * g0[2], f[3] * r * g0[3]); w.z = cvtpk(f[4] * r * g1[0], f[5] * r * g1[1]); w.w = cvtpk(f[6] * r * g1[2], f[7] * r * g1[3]);
;     return __builtin_bit_cast(bf16x8, w);
; }
; template <int BUF>
; __device__ __forceinline__ void fox_tile(f32x16* o, float& m_reg, float& l_reg, const char* lds, const float* ckl, float* al_l, int vb0, const bf16x8* qr, float cq, int qpos, int kb0, bool need_mask, int r32, int hi) {
;     f32x16 p0, p1;
;     qkt<BUF>(p0, p1, lds + 2 * SHM_V, r32, hi, qr);
.LBB0_1366:
	ds_read_b128 v[80:83], v161 offset:288
	s_add_i32 s0, s79, 63
	s_cmp_le_i32 s0, s73
	s_waitcnt lgkmcnt(0)
	v_sub_f32_e32 v133, v69, v81
	v_sub_f32_e32 v132, v68, v80
	v_sub_f32_e32 v131, v71, v83
	v_sub_f32_e32 v130, v70, v82
	ds_read_b128 v[80:83], v161 offset:320
	s_waitcnt lgkmcnt(0)
	v_sub_f32_e32 v127, v73, v81
	v_sub_f32_e32 v126, v72, v80
	v_sub_f32_e32 v125, v75, v83
	v_sub_f32_e32 v124, v74, v82
	ds_read_b128 v[80:83], v162 offset:32768
	s_waitcnt vmcnt(1)
	ds_read_b128 v[96:99], v148
	s_waitcnt lgkmcnt(0)
	s_setprio 3
	v_mfma_f32_32x32x16_bf16 v[80:95], v[80:83], v[96:99], 0
	s_waitcnt vmcnt(0)
	ds_read_b128 v[100:103], v163 offset:32768
	ds_read_b128 v[104:107], v148 offset:1024
	s_waitcnt lgkmcnt(0)
	v_mfma_f32_32x32x16_bf16 v[80:95], v[100:103], v[104:107], v[80:95]
	ds_read_b128 v[100:103], v161 offset:352
	s_waitcnt lgkmcnt(0)
	v_sub_f32_e32 v123, v77, v101
	v_sub_f32_e32 v122, v76, v100
	v_sub_f32_e32 v121, v79, v103
	v_sub_f32_e32 v120, v78, v102
	ds_read_b128 v[100:103], v164 offset:32768
	ds_read_b128 v[108:111], v148 offset:2048
	s_waitcnt lgkmcnt(0)
	v_mfma_f32_32x32x16_bf16 v[80:95], v[100:103], v[108:111], v[80:95]
	ds_read_b128 v[100:103], v161 offset:256
	s_waitcnt lgkmcnt(0)
	v_sub_f32_e32 v135, v67, v103
	v_sub_f32_e32 v134, v66, v102
	v_sub_f32_e32 v137, v65, v101
	v_sub_f32_e32 v136, v64, v100
	ds_read_b128 v[100:103], v165 offset:32768
	ds_read_b128 v[166:169], v148 offset:3072
	s_waitcnt lgkmcnt(0)
	v_mfma_f32_32x32x16_bf16 v[80:95], v[100:103], v[166:169], v[80:95]
	ds_read_b128 v[100:103], v162 offset:32896
	ds_read_b128 v[178:181], v148 offset:4096
	s_waitcnt lgkmcnt(0)
	v_mfma_f32_32x32x16_bf16 v[80:95], v[100:103], v[178:181], v[80:95]
	ds_read_b128 v[100:103], v163 offset:32896
	ds_read_b128 v[182:185], v148 offset:5120
	s_waitcnt lgkmcnt(0)
	v_mfma_f32_32x32x16_bf16 v[80:95], v[100:103], v[182:185], v[80:95]
	ds_read_b128 v[100:103], v164 offset:32896
	ds_read_b128 v[186:189], v148 offset:6144
	s_waitcnt lgkmcnt(0)
	v_mfma_f32_32x32x16_bf16 v[80:95], v[100:103], v[186:189], v[80:95]
	ds_read_b128 v[100:103], v165 offset:32896
	ds_read_b128 v[190:193], v148 offset:7168
	s_waitcnt lgkmcnt(0)
	v_mfma_f32_32x32x16_bf16 v[80:95], v[100:103], v[190:193], v[80:95]
	s_nop 11
	v_pk_add_f32 v[136:137], v[80:81], v[136:137]
	v_pk_add_f32 v[134:135], v[82:83], v[134:135]
	ds_read_b128 v[80:83], v162 offset:40960
	v_pk_add_f32 v[120:121], v[94:95], v[120:121]
	v_pk_add_f32 v[122:123], v[92:93], v[122:123]
	v_pk_add_f32 v[124:125], v[90:91], v[124:125]
	v_pk_add_f32 v[126:127], v[88:89], v[126:127]
	v_pk_add_f32 v[130:131], v[86:87], v[130:131]
	v_pk_add_f32 v[132:133], v[84:85], v[132:133]
	s_waitcnt lgkmcnt(0)
	v_mfma_f32_32x32x16_bf16 v[80:95], v[80:83], v[96:99], 0
	ds_read_b128 v[96:99], v163 offset:40960
	s_waitcnt lgkmcnt(0)
	v_mfma_f32_32x32x16_bf16 v[80:95], v[96:99], v[104:107], v[80:95]
	ds_read_b128 v[96:99], v164 offset:40960
	s_waitcnt lgkmcnt(0)
	v_mfma_f32_32x32x16_bf16 v[80:95], v[96:99], v[108:111], v[80:95]
	ds_read_b128 v[96:99], v165 offset:40960
	s_waitcnt lgkmcnt(0)
	v_mfma_f32_32x32x16_bf16 v[80:95], v[96:99], v[166:169], v[80:95]
	ds_read_b128 v[96:99], v162 offset:41088
	s_waitcnt lgkmcnt(0)
	v_mfma_f32_32x32x16_bf16 v[80:95], v[96:99], v[178:181], v[80:95]
	ds_read_b128 v[96:99], v163 offset:41088
	s_waitcnt lgkmcnt(0)
	v_mfma_f32_32x32x16_bf16 v[80:95], v[96:99], v[182:185], v[80:95]
	ds_read_b128 v[96:99], v164 offset:41088
	s_waitcnt lgkmcnt(0)
	v_mfma_f32_32x32x16_bf16 v[80:95], v[96:99], v[186:189], v[80:95]
	ds_read_b128 v[96:99], v165 offset:41088
	s_waitcnt lgkmcnt(0)
	v_mfma_f32_32x32x16_bf16 v[80:95], v[96:99], v[190:193], v[80:95]
	s_setprio 0
	ds_read_b128 v[96:99], v161 offset:416
	s_waitcnt lgkmcnt(0)
	v_sub_f32_e32 v101, v69, v97
	v_sub_f32_e32 v100, v68, v96
	v_sub_f32_e32 v103, v71, v99
	v_sub_f32_e32 v102, v70, v98
	ds_read_b128 v[96:99], v161 offset:448
	s_nop 4
	v_pk_add_f32 v[84:85], v[84:85], v[100:101]
	v_pk_add_f32 v[86:87], v[86:87], v[102:103]
	s_waitcnt lgkmcnt(0)
	v_sub_f32_e32 v105, v73, v97
	v_sub_f32_e32 v104, v72, v96
	v_sub_f32_e32 v107, v75, v99
	v_sub_f32_e32 v106, v74, v98
	ds_read_b128 v[96:99], v161 offset:480
	v_pk_add_f32 v[90:91], v[90:91], v[106:107]
	v_pk_add_f32 v[88:89], v[88:89], v[104:105]
	s_waitcnt lgkmcnt(0)
	v_sub_f32_e32 v109, v77, v97
	v_sub_f32_e32 v108, v76, v96
	v_sub_f32_e32 v111, v79, v99
	v_sub_f32_e32 v110, v78, v98
	ds_read_b128 v[96:99], v161 offset:384
	v_pk_add_f32 v[92:93], v[92:93], v[108:109]
	s_waitcnt lgkmcnt(0)
	v_sub_f32_e32 v97, v65, v97
	v_sub_f32_e32 v96, v64, v96
	v_pk_add_f32 v[138:139], v[80:81], v[96:97]
	v_pk_add_f32 v[80:81], v[94:95], v[110:111]
	v_lshl_add_u64 v[94:95], v[118:119], 0, v[112:113]
	v_add_co_u32_e32 v96, vcc, 0x11401000, v94
	v_sub_f32_e32 v99, v67, v99
	v_sub_f32_e32 v98, v66, v98
	v_addc_co_u32_e32 v97, vcc, 0, v95, vcc
	v_pk_add_f32 v[82:83], v[82:83], v[98:99]
	v_add_co_u32_e32 v98, vcc, 0x11481000, v94
	s_nop 1
	v_addc_co_u32_e32 v99, vcc, 0, v95, vcc
	v_add_co_u32_e32 v100, vcc, 0x11402000, v94
	s_nop 1
	v_addc_co_u32_e32 v101, vcc, 0, v95, vcc
	v_add_co_u32_e32 v94, vcc, 0x11482000, v94
	s_nop 1
	v_addc_co_u32_e32 v95, vcc, 0, v95, vcc
	global_load_dwordx4 v[108:111], v[96:97], off
	global_load_dwordx4 v[104:107], v[98:99], off
	s_nop 0
	global_load_dwordx4 v[96:99], v[100:101], off
	s_nop 0
	global_load_dwordx4 v[100:103], v[94:95], off
	s_cbranch_scc1 .LBB0_1368
; template <int BUF>
; __device__ __forceinline__ void fox_tile(f32x16* o, float& m_reg, float& l_reg, const char* lds, const float* ckl, float* al_l, int vb0, const bf16x8* qr, float cq, int qpos, int kb0, bool need_mask, int r32, int hi) {
;     ...
;     if (need_mask) { const float NEG = -__builtin_inff(); const int dq = qpos - kb0 - 4 * hi;
; #pragma unroll
;         for (int r = 0; r < 16; ++r) { const int c = (r & 3) + 8 * (r >> 2); if (c > dq) p0[r] = NEG; if (c + 32 > dq) p1[r] = NEG; } }
	v_cmp_gt_i32_e64 s[68:69], 26, v160
	v_cmp_gt_i32_e64 s[70:71], 27, v160
	v_cmp_gt_i32_e64 s[66:67], 25, v160
	s_and_b64 s[68:69], s[70:71], s[68:69]
	v_cmp_gt_i32_e64 s[64:65], 24, v160
	s_and_b64 s[66:67], s[68:69], s[66:67]
	v_cmp_gt_i32_e64 s[62:63], 19, v160
	s_and_b64 s[64:65], s[66:67], s[64:65]
	v_cmp_gt_i32_e64 s[60:61], 18, v160
	s_and_b64 s[62:63], s[64:65], s[62:63]
	v_cmp_gt_i32_e64 s[58:59], 17, v160
	s_and_b64 s[60:61], s[62:63], s[60:61]
	v_cmp_gt_i32_e64 s[56:57], 16, v160
	s_and_b64 s[58:59], s[60:61], s[58:59]
	v_cmp_gt_i32_e64 s[54:55], 11, v160
	s_and_b64 s[56:57], s[58:59], s[56:57]
	v_cmp_gt_i32_e64 s[52:53], 10, v160
	s_and_b64 s[54:55], s[56:57], s[54:55]
	v_cmp_gt_i32_e64 s[50:51], 9, v160
	s_and_b64 s[52:53], s[54:55], s[52:53]
	v_cmp_gt_i32_e64 s[48:49], 8, v160
	s_and_b64 s[50:51], s[52:53], s[50:51]
	v_cmp_gt_i32_e64 s[46:47], 3, v160
	s_and_b64 s[48:49], s[50:51], s[48:49]
	v_cmp_gt_i32_e64 s[44:45], 2, v160
	s_and_b64 s[46:47], s[48:49], s[46:47]
	v_cmp_gt_i32_e64 s[42:43], 1, v160
	s_and_b64 s[44:45], s[46:47], s[44:45]
	v_cmp_gt_i32_e64 s[0:1], 0, v160
	s_and_b64 s[42:43], s[44:45], s[42:43]
	s_and_b64 s[0:1], s[42:43], s[0:1]
	v_cmp_gt_i32_e64 s[38:39], 58, v160
	v_cndmask_b32_e64 v136, v136, v143, s[0:1]
	v_cmp_gt_i32_e64 s[0:1], 59, v160
	v_cmp_gt_i32_e64 s[36:37], 57, v160
	v_cmp_gt_i32_e64 s[34:35], 56, v160
	v_cndmask_b32_e64 v81, v81, v143, s[0:1]
	s_and_b64 s[0:1], s[0:1], s[38:39]
	v_cndmask_b32_e64 v80, v80, v143, s[0:1]
	s_and_b64 s[0:1], s[0:1], s[36:37]
	v_cmp_gt_i32_e64 s[30:31], 51, v160
	v_cndmask_b32_e64 v93, v93, v143, s[0:1]
	s_and_b64 s[0:1], s[0:1], s[34:35]
	v_cmp_gt_i32_e64 s[28:29], 50, v160
	v_cndmask_b32_e64 v92, v92, v143, s[0:1]
	s_and_b64 s[0:1], s[0:1], s[30:31]
	v_cmp_gt_i32_e64 s[26:27], 49, v160
	v_cndmask_b32_e64 v91, v91, v143, s[0:1]
	s_and_b64 s[0:1], s[0:1], s[28:29]
	v_cmp_gt_i32_e64 s[24:25], 48, v160
	v_cndmask_b32_e64 v90, v90, v143, s[0:1]
	s_and_b64 s[0:1], s[0:1], s[26:27]
	v_cmp_gt_i32_e64 s[22:23], 43, v160
	v_cndmask_b32_e64 v89, v89, v143, s[0:1]
	s_and_b64 s[0:1], s[0:1], s[24:25]
	v_cmp_gt_i32_e64 s[20:21], 42, v160
	v_cndmask_b32_e64 v88, v88, v143, s[0:1]
	s_and_b64 s[0:1], s[0:1], s[22:23]
	v_cmp_gt_i32_e64 s[18:19], 41, v160
	v_cndmask_b32_e64 v87, v87, v143, s[0:1]
	s_and_b64 s[0:1], s[0:1], s[20:21]
	v_cmp_gt_i32_e64 s[16:17], 40, v160
	v_cndmask_b32_e64 v86, v86, v143, s[0:1]
	s_and_b64 s[0:1], s[0:1], s[18:19]
	v_cmp_gt_i32_e64 s[14:15], 35, v160
	v_cndmask_b32_e64 v85, v85, v143, s[0:1]
	s_and_b64 s[0:1], s[0:1], s[16:17]
	v_cmp_gt_i32_e64 s[12:13], 34, v160
	v_cndmask_b32_e64 v84, v84, v143, s[0:1]
	s_and_b64 s[0:1], s[0:1], s[14:15]
	v_cmp_gt_i32_e64 s[10:11], 33, v160
	v_cndmask_b32_e64 v83, v83, v143, s[0:1]
	s_and_b64 s[0:1], s[0:1], s[12:13]
	v_cmp_gt_i32_e32 vcc, 32, v160
	v_cndmask_b32_e64 v82, v82, v143, s[0:1]
	s_and_b64 s[0:1], s[0:1], s[10:11]
	s_and_b64 vcc, s[0:1], vcc
	v_cndmask_b32_e64 v121, v121, v143, s[70:71]
	v_cndmask_b32_e64 v120, v120, v143, s[68:69]
	v_cndmask_b32_e64 v123, v123, v143, s[66:67]
	v_cndmask_b32_e64 v122, v122, v143, s[64:65]
	v_cndmask_b32_e64 v125, v125, v143, s[62:63]
	v_cndmask_b32_e64 v124, v124, v143, s[60:61]
	v_cndmask_b32_e64 v127, v127, v143, s[58:59]
	v_cndmask_b32_e64 v126, v126, v143, s[56:57]
	v_cndmask_b32_e64 v131, v131, v143, s[54:55]
	v_cndmask_b32_e64 v130, v130, v143, s[52:53]
	v_cndmask_b32_e64 v133, v133, v143, s[50:51]
	v_cndmask_b32_e64 v132, v132, v143, s[48:49]
	v_cndmask_b32_e64 v135, v135, v143, s[46:47]
	v_cndmask_b32_e64 v134, v134, v143, s[44:45]
	v_cndmask_b32_e64 v137, v137, v143, s[42:43]
	v_cndmask_b32_e64 v139, v139, v143, s[0:1]
	v_cndmask_b32_e32 v138, v138, v143, vcc

; __device__ __forceinline__ unsigned cvtpk(float lo, float hi) { f32x2_t v = {lo, hi}; bf16x2_t b = __builtin_convertvector(v, bf16x2_t); return __builtin_bit_cast(unsigned, b); }
; #define PV_WAIT(n) do { asm volatile("s_waitcnt lgkmcnt(%0)" :: "i"(n) : "memory"); SBAR(); } while (0)
; template <int VB>
; __device__ __forceinline__ void pv_tile(f32x16* o, int vb0, bf16x8 pa0, bf16x8 pa1, bf16x8 pa2, bf16x8 pa3) {
;     ...
;     s16x4 Al0, Al1, Al2, Al3, Ah0, Ah1, Ah2, Ah3, Bl0, Bl1, Bl2, Bl3, Bh0, Bh1, Bh2, Bh3;
;     PV_RD(A, 0); PV_RD(B, 1); PV_WAIT(8); PV_MM(A, 0);
;     PV_RD(A, 2); PV_WAIT(8); PV_MM(B, 1);
;     PV_RD(B, 3); PV_WAIT(8); PV_MM(A, 2);
;     PV_WAIT(0); PV_MM(B, 3);
;     ...
; }
; __device__ __forceinline__ bf16x8 knorm8(bf16x8 x, const float* g) {
;     const v4u xv = __builtin_bit_cast(v4u, x); float f[8];
; #pragma unroll
;     for (int e = 0; e < 4; ++e) { f[2 * e] = __builtin_bit_cast(float, xv[e] << 16); f[2 * e + 1] = __builtin_bit_cast(float, xv[e] & 0xffff0000u); }
;     float s = 0.f;
; #pragma unroll
;     for (int e = 0; e < 8; ++e) s += f[e] * f[e];
;     s += __shfl_xor(s, 1); s += __shfl_xor(s, 2); s += __shfl_xor(s, 4); s += __shfl_xor(s, 8);
;     const float r = __builtin_amdgcn_rsqf(s * (1.0f / 128.0f) + 1e-6f);
;     const f32x4 g0 = *(const f32x4*)g, g1 = *(const f32x4*)(g + 4);
;     v4u w; w.x = cvtpk(f[0] * r * g0[0], f[1] * r * g0[1]); w.y = cvtpk(f[2] * r * g0[2], f[3] * r * g0[3]); w.z = cvtpk(f[4] * r * g1[0], f[5] * r * g1[1]); w.w = cvtpk(f[6] * r * g1[2], f[7] * r * g1[3]);
;     return __builtin_bit_cast(bf16x8, w);
; __device__ __forceinline__ void fox_attn_unit(const Params& P, char* lds, int b, int h, int qb) {
;     ...
;     float m_reg = -1e30f, l_reg = 0.f; f32x16 o[4] = {};
;     __syncthreads();
;     int j_lo; { const float thr = *(const float*)(ws + WS_THR), cq0 = ckl[q0];
;         const bool skip = lane < 4 * qb && ckl[64 * lane + 63] - cq0 > thr; const unsigned long long bm = __ballot(!skip); j_lo = (int)__builtin_ctzll(bm) & ~1; }
;     SLOAD(NT - 1); SWRITE(0);
;     __syncthreads();
;     for (int t = NT - 1; t > j_lo; t -= 2) {
;         SLOAD(t - 1);
;         { const int kb0 = t * 64; fox_tile<0>(o, m_reg, l_reg, lds, ckl, al_l, vb0, qr, cq, qpos, kb0, kb0 + 63 > qlo, r32, hi); }
;         SWRITE(1);
;         __syncthreads();
.LBB0_1372:
	ds_read_b64_tr_b16 v[120:121], v158 offset:0
	ds_read_b64_tr_b16 v[122:123], v158 offset:0x800
	ds_read_b64_tr_b16 v[124:125], v158 offset:0x1000
	ds_read_b64_tr_b16 v[126:127], v158 offset:0x1800
	ds_read_b64_tr_b16 v[130:131], v158 offset:0x2000
	ds_read_b64_tr_b16 v[132:133], v158 offset:0x2800
	ds_read_b64_tr_b16 v[134:135], v158 offset:0x3000
	ds_read_b64_tr_b16 v[136:137], v158 offset:0x3800
	ds_read_b64_tr_b16 v[178:179], v158 offset:0x200
	ds_read_b64_tr_b16 v[180:181], v158 offset:0xa00
	ds_read_b64_tr_b16 v[182:183], v158 offset:0x1200
	ds_read_b64_tr_b16 v[184:185], v158 offset:0x1a00
	ds_read_b64_tr_b16 v[186:187], v158 offset:0x2200
	ds_read_b64_tr_b16 v[188:189], v158 offset:0x2a00
	ds_read_b64_tr_b16 v[190:191], v158 offset:0x3200
	ds_read_b64_tr_b16 v[192:193], v158 offset:0x3a00
	s_waitcnt lgkmcnt(8)
	s_nop 0
	s_setprio 3
	v_mfma_f32_32x32x16_bf16 v[0:15], v[80:83], v[120:123], v[0:15]
	ds_read_b64_tr_b16 v[120:121], v158 offset:0x400
	ds_read_b64_tr_b16 v[122:123], v158 offset:0xc00
	v_mfma_f32_32x32x16_bf16 v[0:15], v[84:87], v[124:127], v[0:15]
	ds_read_b64_tr_b16 v[124:125], v158 offset:0x1400
	ds_read_b64_tr_b16 v[126:127], v158 offset:0x1c00
	v_mfma_f32_32x32x16_bf16 v[0:15], v[88:91], v[130:133], v[0:15]
	ds_read_b64_tr_b16 v[130:131], v158 offset:0x2400
	ds_read_b64_tr_b16 v[132:133], v158 offset:0x2c00
	v_mfma_f32_32x32x16_bf16 v[0:15], v[92:95], v[134:137], v[0:15]
	ds_read_b64_tr_b16 v[134:135], v158 offset:0x3400
	ds_read_b64_tr_b16 v[136:137], v158 offset:0x3c00
	s_waitcnt lgkmcnt(8)
	v_mfma_f32_32x32x16_bf16 v[32:47], v[80:83], v[178:181], v[32:47]
	ds_read_b64_tr_b16 v[178:179], v158 offset:0x600
	ds_read_b64_tr_b16 v[180:181], v158 offset:0xe00
	v_mfma_f32_32x32x16_bf16 v[32:47], v[84:87], v[182:185], v[32:47]
	ds_read_b64_tr_b16 v[182:183], v158 offset:0x1600
	ds_read_b64_tr_b16 v[184:185], v158 offset:0x1e00
	v_mfma_f32_32x32x16_bf16 v[32:47], v[88:91], v[186:189], v[32:47]
	ds_read_b64_tr_b16 v[186:187], v158 offset:0x2600
	ds_read_b64_tr_b16 v[188:189], v158 offset:0x2e00
	v_mfma_f32_32x32x16_bf16 v[32:47], v[92:95], v[190:193], v[32:47]
	ds_read_b64_tr_b16 v[190:191], v158 offset:0x3600
	ds_read_b64_tr_b16 v[192:193], v158 offset:0x3e00
	s_waitcnt lgkmcnt(8)
	v_mfma_f32_32x32x16_bf16 v[48:63], v[80:83], v[120:123], v[48:63]
	s_waitcnt lgkmcnt(0)
	v_mfma_f32_32x32x16_bf16 v[48:63], v[84:87], v[124:127], v[48:63]
	v_mfma_f32_32x32x16_bf16 v[48:63], v[88:91], v[130:133], v[48:63]
	v_mfma_f32_32x32x16_bf16 v[48:63], v[92:95], v[134:137], v[48:63]
	v_mfma_f32_32x32x16_bf16 v[16:31], v[80:83], v[178:181], v[16:31]
	s_waitcnt vmcnt(3)
	v_lshlrev_b32_e32 v124, 16, v108
	v_and_b32_e32 v125, 0xffff0000, v108
	v_lshlrev_b32_e32 v120, 16, v109
	v_and_b32_e32 v121, 0xffff0000, v109
	v_pk_mul_f32 v[126:127], v[124:125], v[124:125]
	v_pk_mul_f32 v[122:123], v[120:121], v[120:121]
	v_add_f32_e32 v126, v126, v127
	v_mfma_f32_32x32x16_bf16 v[16:31], v[84:87], v[182:185], v[16:31]
	v_add_f32_e32 v122, v122, v126
	v_add_f32_e32 v122, v123, v122
	ds_read_b128 v[80:83], v153
	ds_read_b128 v[84:87], v153 offset:16
	s_cmp_gt_i32 s78, s77
	s_cselect_b64 s[74:75], -1, 0
	s_cmp_le_i32 s78, s77
	s_cselect_b64 s[2:3], -1, 0
	v_mfma_f32_32x32x16_bf16 v[16:31], v[88:91], v[186:189], v[16:31]
	v_lshlrev_b32_e32 v88, 16, v111
	v_and_b32_e32 v89, 0xffff0000, v111
	v_mul_f32_e64 v90, v88, v88
	v_mul_f32_e64 v91, v89, v89
	s_and_b64 vcc, exec, s[2:3]
	v_mfma_f32_32x32x16_bf16 v[16:31], v[92:95], v[190:193], v[16:31]
	s_setprio 0
	v_lshlrev_b32_e32 v92, 16, v110
	v_and_b32_e32 v93, 0xffff0000, v110
	v_mul_f32_e64 v94, v92, v92
	v_mul_f32_e64 v95, v93, v93
	v_add_f32_e32 v94, v94, v122
	v_add_f32_e32 v94, v95, v94
	v_add_f32_e32 v90, v90, v94
	v_add_f32_e32 v90, v91, v90
	ds_bpermute_b32 v91, v144, v90
	s_waitcnt lgkmcnt(0)
	v_add_f32_e32 v90, v90, v91
	ds_bpermute_b32 v91, v145, v90
	s_waitcnt lgkmcnt(0)
	v_add_f32_e32 v90, v90, v91
	ds_bpermute_b32 v91, v146, v90
	s_waitcnt lgkmcnt(0)
	v_add_f32_e32 v90, v90, v91
	ds_bpermute_b32 v91, v147, v90
	s_waitcnt lgkmcnt(0)
	v_add_f32_e32 v90, v90, v91
	v_fmamk_f32 v90, v90, 0x3c000000, v141
	v_rsq_f32_e32 v90, v90
	s_nop 0
	v_pk_mul_f32 v[94:95], v[90:91], v[124:125] op_sel_hi:[0,1]
	s_waitcnt vmcnt(2)
	v_lshlrev_b32_e32 v124, 16, v104
	v_and_b32_e32 v125, 0xffff0000, v104
	v_pk_mul_f32 v[80:81], v[80:81], v[94:95]
	v_pk_mul_f32 v[94:95], v[90:91], v[120:121] op_sel_hi:[0,1]
	v_lshlrev_b32_e32 v120, 16, v105
	v_and_b32_e32 v121, 0xffff0000, v105
	v_pk_mul_f32 v[126:127], v[124:125], v[124:125]
	v_pk_mul_f32 v[82:83], v[82:83], v[94:95]
	v_pk_mul_f32 v[122:123], v[120:121], v[120:121]
	v_add_f32_e32 v126, v126, v127
	v_cvt_pk_bf16_f32 v80, v80, v81
	v_cvt_pk_bf16_f32 v81, v82, v83
	v_pk_mul_f32 v[82:83], v[90:91], v[92:93] op_sel_hi:[0,1]
	v_lshlrev_b32_e32 v92, 16, v106
	v_and_b32_e32 v93, 0xffff0000, v106
	v_add_f32_e32 v122, v122, v126
	v_pk_mul_f32 v[94:95], v[92:93], v[92:93]
	v_add_f32_e32 v122, v123, v122
	v_pk_mul_f32 v[82:83], v[84:85], v[82:83]
	v_pk_mul_f32 v[84:85], v[90:91], v[88:89] op_sel_hi:[0,1]
	v_lshlrev_b32_e32 v88, 16, v107
	v_and_b32_e32 v89, 0xffff0000, v107
	v_add_f32_e32 v94, v94, v122
	v_pk_mul_f32 v[90:91], v[88:89], v[88:89]
	v_add_f32_e32 v94, v95, v94
	v_add_f32_e32 v90, v90, v94
	v_add_f32_e32 v90, v91, v90
	ds_bpermute_b32 v91, v144, v90
	v_pk_mul_f32 v[84:85], v[86:87], v[84:85]
	v_cvt_pk_bf16_f32 v82, v82, v83
	v_cvt_pk_bf16_f32 v83, v84, v85
	ds_write_b128 v154, v[80:83] offset:49152
	s_waitcnt lgkmcnt(1)
	v_add_f32_e32 v90, v90, v91
	ds_bpermute_b32 v91, v145, v90
	ds_read_b128 v[80:83], v153
	ds_read_b128 v[84:87], v153 offset:16
	s_waitcnt lgkmcnt(2)
	v_add_f32_e32 v90, v90, v91
	ds_bpermute_b32 v91, v146, v90
	s_waitcnt lgkmcnt(0)
	v_add_f32_e32 v90, v90, v91
	ds_bpermute_b32 v91, v147, v90
	s_waitcnt lgkmcnt(0)
	v_add_f32_e32 v90, v90, v91
	v_fmamk_f32 v90, v90, 0x3c000000, v141
	v_rsq_f32_e32 v90, v90
	s_nop 0
	v_pk_mul_f32 v[94:95], v[90:91], v[124:125] op_sel_hi:[0,1]
	v_pk_mul_f32 v[80:81], v[80:81], v[94:95]
	v_pk_mul_f32 v[94:95], v[90:91], v[120:121] op_sel_hi:[0,1]
	v_pk_mul_f32 v[82:83], v[82:83], v[94:95]
	v_cvt_pk_bf16_f32 v80, v80, v81
	v_cvt_pk_bf16_f32 v81, v82, v83
	v_pk_mul_f32 v[82:83], v[90:91], v[92:93] op_sel_hi:[0,1]
	v_pk_mul_f32 v[82:83], v[84:85], v[82:83]
	v_pk_mul_f32 v[84:85], v[90:91], v[88:89] op_sel_hi:[0,1]
	v_pk_mul_f32 v[84:85], v[86:87], v[84:85]
	v_cvt_pk_bf16_f32 v82, v82, v83
	v_cvt_pk_bf16_f32 v83, v84, v85
	ds_write_b128 v154, v[80:83] offset:57344
	s_waitcnt vmcnt(1)
	ds_write_b128 v156, v[96:99] offset:16384
	s_waitcnt vmcnt(0)
	ds_write_b128 v157, v[100:103] offset:16384
	s_waitcnt lgkmcnt(0)
	s_barrier
; template <int KB>
; __device__ __forceinline__ void qkt(f32x16& p0, f32x16& p1, const char* K_lds, int r32, int hi, const bf16x8* qs) {
;     p0 = f32x16{}; p1 = f32x16{};
;     const char* kb[4];
; #pragma unroll
;     for (int dd = 0; dd < 4; ++dd) kb[dd] = K_lds + KB * SHM_K + KSWZ(r32, (dd * 16 + hi * 8) * 2);
; #pragma unroll
;     for (int d0 = 0; d0 < 8; ++d0) { const char* a = kb[d0 & 3] + (d0 >> 2) * 128;
;         bf16x8 b0 = *reinterpret_cast<const bf16x8*>(a);
;         bf16x8 b1 = *reinterpret_cast<const bf16x8*>(a + 32 * 256);
;         const bf16x8 qf = qs[d0 * 64];
;         p0 = __builtin_amdgcn_mfma_f32_32x32x16_bf16(b0, qf, p0, 0, 0, 0);
;         p1 = __builtin_amdgcn_mfma_f32_32x32x16_bf16(b1, qf, p1, 0, 0, 0); }
; }
; template <int VB>
; __device__ __forceinline__ void pv_tile(f32x16* o, int vb0, bf16x8 pa0, bf16x8 pa1, bf16x8 pa2, bf16x8 pa3) {
;     ...
;     s16x4 Al0, Al1, Al2, Al3, Ah0, Ah1, Ah2, Ah3, Bl0, Bl1, Bl2, Bl3, Bh0, Bh1, Bh2, Bh3;
;     PV_RD(A, 0); PV_RD(B, 1); PV_WAIT(8); PV_MM(A, 0);
;     PV_RD(A, 2); PV_WAIT(8); PV_MM(B, 1);
;     PV_RD(B, 3); PV_WAIT(8); PV_MM(A, 2);
;     PV_WAIT(0); PV_MM(B, 3);
;     ...
; }
; __device__ __forceinline__ bf16x8 knorm8(bf16x8 x, const float* g) {
;     const v4u xv = __builtin_bit_cast(v4u, x); float f[8];
; #pragma unroll
;     for (int e = 0; e < 4; ++e) { f[2 * e] = __builtin_bit_cast(float, xv[e] << 16); f[2 * e + 1] = __builtin_bit_cast(float, xv[e] & 0xffff0000u); }
;     float s = 0.f;
; #pragma unroll
;     for (int e = 0; e < 8; ++e) s += f[e] * f[e];
;     s += __shfl_xor(s, 1); s += __shfl_xor(s, 2); s += __shfl_xor(s, 4); s += __shfl_xor(s, 8);
;     const float r = __builtin_amdgcn_rsqf(s * (1.0f / 128.0f) + 1e-6f);
;     const f32x4 g0 = *(const f32x4*)g, g1 = *(const f32x4*)(g + 4);
;     v4u w; w.x = cvtpk(f[0] * r * g0[0], f[1] * r * g0[1]); w.y = cvtpk(f[2] * r * g0[2], f[3] * r * g0[3]); w.z = cvtpk(f[4] * r * g1[0], f[5] * r * g1[1]); w.w = cvtpk(f[6] * r * g1[2], f[7] * r * g1[3]);
;     return __builtin_bit_cast(bf16x8, w);
; }
; template <int BUF>
; __device__ __forceinline__ void fox_tile(f32x16* o, float& m_reg, float& l_reg, const char* lds, const float* ckl, float* al_l, int vb0, const bf16x8* qr, float cq, int qpos, int kb0, bool need_mask, int r32, int hi) {
;     f32x16 p0, p1;
;     qkt<BUF>(p0, p1, lds + 2 * SHM_V, r32, hi, qr);
	s_cbranch_vccnz .LBB0_1374
	v_lshl_add_u64 v[80:81], v[116:117], 0, v[112:113]
	v_add_co_u32_e32 v82, vcc, 0x11401000, v80
	s_nop 1
	v_addc_co_u32_e32 v83, vcc, 0, v81, vcc
	v_add_co_u32_e32 v84, vcc, 0x11481000, v80
	s_nop 1
	v_addc_co_u32_e32 v85, vcc, 0, v81, vcc
	global_load_dwordx4 v[108:111], v[82:83], off
	global_load_dwordx4 v[104:107], v[84:85], off
	v_add_co_u32_e32 v82, vcc, 0x11402000, v80
	s_nop 1
	v_addc_co_u32_e32 v83, vcc, 0, v81, vcc
	v_add_co_u32_e32 v80, vcc, 0x11482000, v80
	s_nop 1
	v_addc_co_u32_e32 v81, vcc, 0, v81, vcc
	global_load_dwordx4 v[96:99], v[82:83], off
	global_load_dwordx4 v[100:103], v[80:81], off
.LBB0_1374:
	ds_read_b128 v[80:83], v161 offset:32
	s_cmp_le_i32 s79, s82
	s_waitcnt lgkmcnt(0)
	v_sub_f32_e32 v133, v69, v81
	v_sub_f32_e32 v132, v68, v80
	v_sub_f32_e32 v131, v71, v83
	v_sub_f32_e32 v130, v70, v82
	ds_read_b128 v[80:83], v161 offset:64
	s_waitcnt lgkmcnt(0)
	v_sub_f32_e32 v127, v73, v81
	v_sub_f32_e32 v126, v72, v80
	v_sub_f32_e32 v125, v75, v83
	v_sub_f32_e32 v124, v74, v82
	ds_read_b128 v[80:83], v162 offset:49152
	ds_read_b128 v[178:181], v148
	s_waitcnt lgkmcnt(0)
	s_setprio 3
	v_mfma_f32_32x32x16_bf16 v[80:95], v[80:83], v[178:181], 0
	ds_read_b128 v[120:123], v163 offset:49152
	ds_read_b128 v[182:185], v148 offset:1024
	s_waitcnt lgkmcnt(0)
	v_mfma_f32_32x32x16_bf16 v[80:95], v[120:123], v[182:185], v[80:95]
	ds_read_b128 v[120:123], v161 offset:96
	s_waitcnt lgkmcnt(0)
	v_sub_f32_e32 v135, v77, v121
	v_sub_f32_e32 v134, v76, v120
	v_sub_f32_e32 v139, v79, v123
	v_sub_f32_e32 v138, v78, v122
	ds_read_b128 v[120:123], v164 offset:49152
	ds_read_b128 v[186:189], v148 offset:2048
	s_waitcnt lgkmcnt(0)
	v_mfma_f32_32x32x16_bf16 v[80:95], v[120:123], v[186:189], v[80:95]
	ds_read_b128 v[120:123], v161
	s_waitcnt lgkmcnt(0)
	v_sub_f32_e32 v171, v67, v123
	v_sub_f32_e32 v170, v66, v122
	v_sub_f32_e32 v137, v65, v121
	v_sub_f32_e32 v136, v64, v120
	ds_read_b128 v[120:123], v165 offset:49152
	ds_read_b128 v[190:193], v148 offset:3072
	s_waitcnt lgkmcnt(0)
	v_mfma_f32_32x32x16_bf16 v[80:95], v[120:123], v[190:193], v[80:95]
	ds_read_b128 v[120:123], v162 offset:49280
	ds_read_b128 v[194:197], v148 offset:4096
	s_waitcnt lgkmcnt(0)
	v_mfma_f32_32x32x16_bf16 v[80:95], v[120:123], v[194:197], v[80:95]
	ds_read_b128 v[120:123], v163 offset:49280
	ds_read_b128 v[198:201], v148 offset:5120
	s_waitcnt lgkmcnt(0)
	v_mfma_f32_32x32x16_bf16 v[80:95], v[120:123], v[198:201], v[80:95]
	ds_read_b128 v[120:123], v164 offset:49280
	ds_read_b128 v[202:205], v148 offset:6144
	s_waitcnt lgkmcnt(0)
	v_mfma_f32_32x32x16_bf16 v[80:95], v[120:123], v[202:205], v[80:95]
	ds_read_b128 v[120:123], v165 offset:49280
	ds_read_b128 v[206:209], v148 offset:7168
	s_waitcnt lgkmcnt(0)
	v_mfma_f32_32x32x16_bf16 v[80:95], v[120:123], v[206:209], v[80:95]
	s_nop 11
	v_pk_add_f32 v[136:137], v[80:81], v[136:137]
	v_pk_add_f32 v[122:123], v[92:93], v[134:135]
	v_pk_add_f32 v[134:135], v[82:83], v[170:171]
	ds_read_b128 v[80:83], v162 offset:57344
	v_pk_add_f32 v[120:121], v[94:95], v[138:139]
	v_pk_add_f32 v[124:125], v[90:91], v[124:125]
	v_pk_add_f32 v[126:127], v[88:89], v[126:127]
	v_pk_add_f32 v[130:131], v[86:87], v[130:131]
	v_pk_add_f32 v[132:133], v[84:85], v[132:133]
	s_waitcnt lgkmcnt(0)
	v_mfma_f32_32x32x16_bf16 v[80:95], v[80:83], v[178:181], 0
	ds_read_b128 v[178:181], v163 offset:57344
	s_waitcnt lgkmcnt(0)
	v_mfma_f32_32x32x16_bf16 v[80:95], v[178:181], v[182:185], v[80:95]
	ds_read_b128 v[178:181], v164 offset:57344
	s_waitcnt lgkmcnt(0)
	v_mfma_f32_32x32x16_bf16 v[80:95], v[178:181], v[186:189], v[80:95]
	ds_read_b128 v[178:181], v165 offset:57344
	s_waitcnt lgkmcnt(0)
	v_mfma_f32_32x32x16_bf16 v[80:95], v[178:181], v[190:193], v[80:95]
	ds_read_b128 v[178:181], v162 offset:57472
	s_waitcnt lgkmcnt(0)
	v_mfma_f32_32x32x16_bf16 v[80:95], v[178:181], v[194:197], v[80:95]
	ds_read_b128 v[178:181], v163 offset:57472
	s_waitcnt lgkmcnt(0)
	v_mfma_f32_32x32x16_bf16 v[80:95], v[178:181], v[198:201], v[80:95]
	ds_read_b128 v[178:181], v164 offset:57472
	s_waitcnt lgkmcnt(0)
	v_mfma_f32_32x32x16_bf16 v[80:95], v[178:181], v[202:205], v[80:95]
	ds_read_b128 v[178:181], v165 offset:57472
	s_waitcnt lgkmcnt(0)
	v_mfma_f32_32x32x16_bf16 v[80:95], v[178:181], v[206:209], v[80:95]
	s_setprio 0
	ds_read_b128 v[178:181], v161 offset:160
	s_waitcnt lgkmcnt(0)
	v_sub_f32_e32 v171, v69, v179
	v_sub_f32_e32 v170, v68, v178
	v_sub_f32_e32 v183, v71, v181
	v_sub_f32_e32 v182, v70, v180
	ds_read_b128 v[178:181], v161 offset:192
	s_nop 4
	v_pk_add_f32 v[86:87], v[86:87], v[182:183]
	v_pk_add_f32 v[84:85], v[84:85], v[170:171]
	s_waitcnt lgkmcnt(0)
	v_sub_f32_e32 v185, v73, v179
	v_sub_f32_e32 v184, v72, v178
	v_sub_f32_e32 v187, v75, v181
	v_sub_f32_e32 v186, v74, v180
	ds_read_b128 v[178:181], v161 offset:224
	v_pk_add_f32 v[90:91], v[90:91], v[186:187]
	v_pk_add_f32 v[88:89], v[88:89], v[184:185]
	s_waitcnt lgkmcnt(0)
	v_sub_f32_e32 v189, v77, v179
	v_sub_f32_e32 v188, v76, v178
	v_sub_f32_e32 v191, v79, v181
	v_sub_f32_e32 v190, v78, v180
	ds_read_b128 v[178:181], v161 offset:128
	v_pk_add_f32 v[92:93], v[92:93], v[188:189]
	s_waitcnt lgkmcnt(0)
	v_sub_f32_e32 v181, v67, v181
	v_sub_f32_e32 v180, v66, v180
	v_sub_f32_e32 v139, v65, v179
	v_sub_f32_e32 v138, v64, v178
	v_pk_add_f32 v[138:139], v[80:81], v[138:139]
	v_pk_add_f32 v[80:81], v[94:95], v[190:191]
	v_pk_add_f32 v[82:83], v[82:83], v[180:181]
	s_cbranch_scc1 .LBB0_1376
; template <int BUF>
; __device__ __forceinline__ void fox_tile(f32x16* o, float& m_reg, float& l_reg, const char* lds, const float* ckl, float* al_l, int vb0, const bf16x8* qr, float cq, int qpos, int kb0, bool need_mask, int r32, int hi) {
;     ...
;     if (need_mask) { const float NEG = -__builtin_inff(); const int dq = qpos - kb0 - 4 * hi;
; #pragma unroll
;         for (int r = 0; r < 16; ++r) { const int c = (r & 3) + 8 * (r >> 2); if (c > dq) p0[r] = NEG; if (c + 32 > dq) p1[r] = NEG; } }
	v_add_u32_e32 v94, 64, v160
	v_cmp_gt_i32_e64 s[68:69], 26, v94
	v_cmp_gt_i32_e64 s[70:71], 27, v94
	v_cmp_gt_i32_e64 s[66:67], 25, v94
	s_and_b64 s[68:69], s[70:71], s[68:69]
	v_cmp_gt_i32_e64 s[64:65], 24, v94
	s_and_b64 s[66:67], s[68:69], s[66:67]
	v_cmp_gt_i32_e64 s[62:63], 19, v94
	s_and_b64 s[64:65], s[66:67], s[64:65]
	v_cmp_gt_i32_e64 s[60:61], 18, v94
	s_and_b64 s[62:63], s[64:65], s[62:63]
	v_cmp_gt_i32_e64 s[58:59], 17, v94
	s_and_b64 s[60:61], s[62:63], s[60:61]
	v_cmp_gt_i32_e64 s[56:57], 16, v94
	s_and_b64 s[58:59], s[60:61], s[58:59]
	v_cmp_gt_i32_e64 s[54:55], 11, v94
	s_and_b64 s[56:57], s[58:59], s[56:57]
	v_cmp_gt_i32_e64 s[52:53], 10, v94
	s_and_b64 s[54:55], s[56:57], s[54:55]
	v_cmp_gt_i32_e64 s[50:51], 9, v94
	s_and_b64 s[52:53], s[54:55], s[52:53]
	v_cmp_gt_i32_e64 s[48:49], 8, v94
	s_and_b64 s[50:51], s[52:53], s[50:51]
	v_cmp_gt_i32_e64 s[46:47], 3, v94
	s_and_b64 s[48:49], s[50:51], s[48:49]
	v_cmp_gt_i32_e64 s[44:45], 2, v94
	s_and_b64 s[46:47], s[48:49], s[46:47]
	v_cmp_gt_i32_e64 s[42:43], 1, v94
	s_and_b64 s[44:45], s[46:47], s[44:45]
	v_cmp_gt_i32_e64 s[0:1], 0, v94
	s_and_b64 s[42:43], s[44:45], s[42:43]
	s_and_b64 s[0:1], s[42:43], s[0:1]
	v_cmp_gt_i32_e64 s[38:39], 58, v94
	v_cndmask_b32_e64 v136, v136, v143, s[0:1]
	v_cmp_gt_i32_e64 s[0:1], 59, v94
	v_cmp_gt_i32_e64 s[36:37], 57, v94
	v_cmp_gt_i32_e64 s[34:35], 56, v94
	v_cndmask_b32_e64 v81, v81, v143, s[0:1]
	s_and_b64 s[0:1], s[0:1], s[38:39]
	v_cndmask_b32_e64 v80, v80, v143, s[0:1]
	s_and_b64 s[0:1], s[0:1], s[36:37]
	v_cmp_gt_i32_e64 s[30:31], 51, v94
	v_cndmask_b32_e64 v93, v93, v143, s[0:1]
	s_and_b64 s[0:1], s[0:1], s[34:35]
	v_cmp_gt_i32_e64 s[28:29], 50, v94
	v_cndmask_b32_e64 v92, v92, v143, s[0:1]
	s_and_b64 s[0:1], s[0:1], s[30:31]
	v_cmp_gt_i32_e64 s[26:27], 49, v94
	v_cndmask_b32_e64 v91, v91, v143, s[0:1]
	s_and_b64 s[0:1], s[0:1], s[28:29]
	v_cmp_gt_i32_e64 s[24:25], 48, v94
	v_cndmask_b32_e64 v90, v90, v143, s[0:1]
	s_and_b64 s[0:1], s[0:1], s[26:27]
	v_cmp_gt_i32_e64 s[22:23], 43, v94
	v_cndmask_b32_e64 v89, v89, v143, s[0:1]
	s_and_b64 s[0:1], s[0:1], s[24:25]
	v_cmp_gt_i32_e64 s[20:21], 42, v94
	v_cndmask_b32_e64 v88, v88, v143, s[0:1]
	s_and_b64 s[0:1], s[0:1], s[22:23]
	v_cmp_gt_i32_e64 s[18:19], 41, v94
	v_cndmask_b32_e64 v87, v87, v143, s[0:1]
	s_and_b64 s[0:1], s[0:1], s[20:21]
	v_cmp_gt_i32_e64 s[16:17], 40, v94
	v_cndmask_b32_e64 v86, v86, v143, s[0:1]
	s_and_b64 s[0:1], s[0:1], s[18:19]
	v_cmp_gt_i32_e64 s[14:15], 35, v94
	v_cndmask_b32_e64 v85, v85, v143, s[0:1]
	s_and_b64 s[0:1], s[0:1], s[16:17]
	v_cmp_gt_i32_e64 s[12:13], 34, v94
	v_cndmask_b32_e64 v84, v84, v143, s[0:1]
	s_and_b64 s[0:1], s[0:1], s[14:15]
	v_cmp_gt_i32_e64 s[10:11], 33, v94
	v_cndmask_b32_e64 v83, v83, v143, s[0:1]
	s_and_b64 s[0:1], s[0:1], s[12:13]
	v_cmp_gt_i32_e32 vcc, 32, v94
	v_cndmask_b32_e64 v82, v82, v143, s[0:1]
	s_and_b64 s[0:1], s[0:1], s[10:11]
	s_and_b64 vcc, s[0:1], vcc
	v_cndmask_b32_e64 v121, v121, v143, s[70:71]
	v_cndmask_b32_e64 v120, v120, v143, s[68:69]
	v_cndmask_b32_e64 v123, v123, v143, s[66:67]
	v_cndmask_b32_e64 v122, v122, v143, s[64:65]
	v_cndmask_b32_e64 v125, v125, v143, s[62:63]
	v_cndmask_b32_e64 v124, v124, v143, s[60:61]
	v_cndmask_b32_e64 v127, v127, v143, s[58:59]
	v_cndmask_b32_e64 v126, v126, v143, s[56:57]
	v_cndmask_b32_e64 v131, v131, v143, s[54:55]
	v_cndmask_b32_e64 v130, v130, v143, s[52:53]
	v_cndmask_b32_e64 v133, v133, v143, s[50:51]
	v_cndmask_b32_e64 v132, v132, v143, s[48:49]
	v_cndmask_b32_e64 v135, v135, v143, s[46:47]
	v_cndmask_b32_e64 v134, v134, v143, s[44:45]
	v_cndmask_b32_e64 v137, v137, v143, s[42:43]
	v_cndmask_b32_e64 v139, v139, v143, s[0:1]
	v_cndmask_b32_e32 v138, v138, v143, vcc

; __device__ __forceinline__ unsigned cvtpk(float lo, float hi) { f32x2_t v = {lo, hi}; bf16x2_t b = __builtin_convertvector(v, bf16x2_t); return __builtin_bit_cast(unsigned, b); }
; #define PV_RD(S, d0) do { constexpr int b_ = VB * SHM_V + v_rd_off(d0, 0, 0); \
;         TRRD(S##l0, b_); TRRD(S##h0, b_ + 2048); TRRD(S##l1, b_ + 4096); TRRD(S##h1, b_ + 6144); TRRD(S##l2, b_ + 8192); TRRD(S##h2, b_ + 10240); TRRD(S##l3, b_ + 12288); TRRD(S##h3, b_ + 14336); } while (0)
; #define PV_WAIT(n) do { asm volatile("s_waitcnt lgkmcnt(%0)" :: "i"(n) : "memory"); SBAR(); } while (0)
; template <int VB>
; __device__ __forceinline__ void pv_tile(f32x16* o, int vb0, bf16x8 pa0, bf16x8 pa1, bf16x8 pa2, bf16x8 pa3) {
;     ...
;     s16x4 Al0, Al1, Al2, Al3, Ah0, Ah1, Ah2, Ah3, Bl0, Bl1, Bl2, Bl3, Bh0, Bh1, Bh2, Bh3;
;     PV_RD(A, 0); PV_RD(B, 1); PV_WAIT(8); PV_MM(A, 0);
;     PV_RD(A, 2); PV_WAIT(8); PV_MM(B, 1);
;     PV_RD(B, 3); PV_WAIT(8); PV_MM(A, 2);
;     PV_WAIT(0); PV_MM(B, 3);
;     ...
; }
; __device__ __forceinline__ bf16x8 knorm8(bf16x8 x, const float* g) {
;     const v4u xv = __builtin_bit_cast(v4u, x); float f[8];
; #pragma unroll
;     for (int e = 0; e < 4; ++e) { f[2 * e] = __builtin_bit_cast(float, xv[e] << 16); f[2 * e + 1] = __builtin_bit_cast(float, xv[e] & 0xffff0000u); }
;     float s = 0.f;
; #pragma unroll
;     for (int e = 0; e < 8; ++e) s += f[e] * f[e];
;     s += __shfl_xor(s, 1); s += __shfl_xor(s, 2); s += __shfl_xor(s, 4); s += __shfl_xor(s, 8);
;     const float r = __builtin_amdgcn_rsqf(s * (1.0f / 128.0f) + 1e-6f);
;     const f32x4 g0 = *(const f32x4*)g, g1 = *(const f32x4*)(g + 4);
;     v4u w; w.x = cvtpk(f[0] * r * g0[0], f[1] * r * g0[1]); w.y = cvtpk(f[2] * r * g0[2], f[3] * r * g0[3]); w.z = cvtpk(f[4] * r * g1[0], f[5] * r * g1[1]); w.w = cvtpk(f[6] * r * g1[2], f[7] * r * g1[3]);
;     return __builtin_bit_cast(bf16x8, w);
; __device__ __forceinline__ void fox_attn_unit(const Params& P, char* lds, int b, int h, int qb) {
;     ...
;         { const int kb0 = (t - 1) * 64; fox_tile<1>(o, m_reg, l_reg, lds, ckl, al_l, vb0, qr, cq, qpos, kb0, kb0 + 63 > qlo, r32, hi); }
;         if (t - 2 > j_lo) SWRITE(0);
.LBB0_1380:
	ds_read_b64_tr_b16 v[124:125], v158 offset:0x4000
	ds_read_b64_tr_b16 v[126:127], v158 offset:0x4800
	ds_read_b64_tr_b16 v[130:131], v158 offset:0x5000
	ds_read_b64_tr_b16 v[132:133], v158 offset:0x5800
	ds_read_b64_tr_b16 v[134:135], v158 offset:0x6000
	ds_read_b64_tr_b16 v[136:137], v158 offset:0x6800
	ds_read_b64_tr_b16 v[178:179], v158 offset:0x7000
	ds_read_b64_tr_b16 v[180:181], v158 offset:0x7800
	ds_read_b64_tr_b16 v[182:183], v158 offset:0x4200
	ds_read_b64_tr_b16 v[184:185], v158 offset:0x4a00
	ds_read_b64_tr_b16 v[186:187], v158 offset:0x5200
	ds_read_b64_tr_b16 v[188:189], v158 offset:0x5a00
	ds_read_b64_tr_b16 v[190:191], v158 offset:0x6200
	ds_read_b64_tr_b16 v[192:193], v158 offset:0x6a00
	ds_read_b64_tr_b16 v[194:195], v158 offset:0x7200
	ds_read_b64_tr_b16 v[196:197], v158 offset:0x7a00
	s_waitcnt lgkmcnt(8)
	s_nop 0
	s_setprio 3
	v_mfma_f32_32x32x16_bf16 v[0:15], v[80:83], v[124:127], v[0:15]
	ds_read_b64_tr_b16 v[124:125], v158 offset:0x4400
	ds_read_b64_tr_b16 v[126:127], v158 offset:0x4c00
	v_mfma_f32_32x32x16_bf16 v[0:15], v[84:87], v[130:133], v[0:15]
	ds_read_b64_tr_b16 v[130:131], v158 offset:0x5400
	ds_read_b64_tr_b16 v[132:133], v158 offset:0x5c00
	v_mfma_f32_32x32x16_bf16 v[0:15], v[88:91], v[134:137], v[0:15]
	ds_read_b64_tr_b16 v[134:135], v158 offset:0x6400
	ds_read_b64_tr_b16 v[136:137], v158 offset:0x6c00
	v_mfma_f32_32x32x16_bf16 v[0:15], v[92:95], v[178:181], v[0:15]
	ds_read_b64_tr_b16 v[178:179], v158 offset:0x7400
	ds_read_b64_tr_b16 v[180:181], v158 offset:0x7c00
	s_waitcnt lgkmcnt(8)
	v_mfma_f32_32x32x16_bf16 v[32:47], v[80:83], v[182:185], v[32:47]
	ds_read_b64_tr_b16 v[182:183], v158 offset:0x4600
	ds_read_b64_tr_b16 v[184:185], v158 offset:0x4e00
	v_mfma_f32_32x32x16_bf16 v[32:47], v[84:87], v[186:189], v[32:47]
	ds_read_b64_tr_b16 v[186:187], v158 offset:0x5600
	ds_read_b64_tr_b16 v[188:189], v158 offset:0x5e00
	v_mfma_f32_32x32x16_bf16 v[32:47], v[88:91], v[190:193], v[32:47]
	ds_read_b64_tr_b16 v[190:191], v158 offset:0x6600
	ds_read_b64_tr_b16 v[192:193], v158 offset:0x6e00
	v_mfma_f32_32x32x16_bf16 v[32:47], v[92:95], v[194:197], v[32:47]
	ds_read_b64_tr_b16 v[194:195], v158 offset:0x7600
	ds_read_b64_tr_b16 v[196:197], v158 offset:0x7e00
	s_waitcnt lgkmcnt(8)
	v_mfma_f32_32x32x16_bf16 v[48:63], v[80:83], v[124:127], v[48:63]
	s_waitcnt lgkmcnt(0)
	v_mfma_f32_32x32x16_bf16 v[48:63], v[84:87], v[130:133], v[48:63]
	v_mfma_f32_32x32x16_bf16 v[48:63], v[88:91], v[134:137], v[48:63]
	v_mfma_f32_32x32x16_bf16 v[48:63], v[92:95], v[178:181], v[48:63]
	v_mfma_f32_32x32x16_bf16 v[16:31], v[80:83], v[182:185], v[16:31]
	s_andn2_b64 vcc, exec, s[74:75]
	v_mfma_f32_32x32x16_bf16 v[16:31], v[84:87], v[186:189], v[16:31]
	v_mfma_f32_32x32x16_bf16 v[16:31], v[88:91], v[190:193], v[16:31]
	v_mfma_f32_32x32x16_bf16 v[16:31], v[92:95], v[194:197], v[16:31]
	s_setprio 0
	s_cbranch_vccnz .LBB0_1365
	s_waitcnt vmcnt(3)
	v_lshlrev_b32_e32 v94, 16, v108
	v_and_b32_e32 v95, 0xffff0000, v108
	v_lshlrev_b32_e32 v92, 16, v109
	v_and_b32_e32 v93, 0xffff0000, v109
	v_pk_mul_f32 v[86:87], v[94:95], v[94:95]
	v_pk_mul_f32 v[84:85], v[92:93], v[92:93]
	v_add_f32_e32 v86, v86, v87
	v_lshlrev_b32_e32 v90, 16, v110
	v_and_b32_e32 v91, 0xffff0000, v110
	v_add_f32_e32 v84, v84, v86
	v_pk_mul_f32 v[82:83], v[90:91], v[90:91]
	v_add_f32_e32 v84, v85, v84
	v_lshlrev_b32_e32 v88, 16, v111
	v_and_b32_e32 v89, 0xffff0000, v111
	v_add_f32_e32 v82, v82, v84
	v_pk_mul_f32 v[80:81], v[88:89], v[88:89]
	v_add_f32_e32 v82, v83, v82
	v_add_f32_e32 v80, v80, v82
	v_add_f32_e32 v80, v81, v80
	ds_bpermute_b32 v81, v144, v80
	s_waitcnt vmcnt(2)
	v_lshlrev_b32_e32 v126, 16, v104
	v_and_b32_e32 v127, 0xffff0000, v104
	v_lshlrev_b32_e32 v124, 16, v105
	v_and_b32_e32 v125, 0xffff0000, v105
	s_waitcnt lgkmcnt(0)
	v_add_f32_e32 v80, v80, v81
	ds_bpermute_b32 v81, v145, v80
	v_pk_mul_f32 v[86:87], v[126:127], v[126:127]
	v_lshlrev_b32_e32 v110, 16, v106
	v_and_b32_e32 v111, 0xffff0000, v106
	v_add_f32_e32 v86, v86, v87
	s_waitcnt lgkmcnt(0)
	v_add_f32_e32 v80, v80, v81
	ds_bpermute_b32 v81, v146, v80
	v_pk_mul_f32 v[82:83], v[110:111], v[110:111]
	v_lshlrev_b32_e32 v108, 16, v107
	v_and_b32_e32 v109, 0xffff0000, v107
	s_waitcnt lgkmcnt(0)
	v_add_f32_e32 v84, v80, v81
	ds_bpermute_b32 v85, v147, v84
	v_pk_mul_f32 v[80:81], v[108:109], v[108:109]
	s_waitcnt lgkmcnt(0)
	v_add_f32_e32 v84, v84, v85
	v_fmamk_f32 v84, v84, 0x3c000000, v141
	v_rsq_f32_e32 v106, v84
	v_pk_mul_f32 v[84:85], v[124:125], v[124:125]
	v_pk_mul_f32 v[92:93], v[106:107], v[92:93] op_sel_hi:[0,1]
	v_add_f32_e32 v84, v84, v86
	v_add_f32_e32 v84, v85, v84
	v_add_f32_e32 v82, v82, v84
	v_add_f32_e32 v82, v83, v82
	v_add_f32_e32 v80, v80, v82
	v_add_f32_e32 v104, v81, v80
	ds_bpermute_b32 v105, v144, v104
	ds_read_b128 v[80:83], v153
	ds_read_b128 v[84:87], v153 offset:16
	v_pk_mul_f32 v[94:95], v[106:107], v[94:95] op_sel_hi:[0,1]
	s_waitcnt lgkmcnt(2)
	v_add_f32_e32 v104, v104, v105
	ds_bpermute_b32 v105, v145, v104
	s_waitcnt lgkmcnt(2)
	v_pk_mul_f32 v[82:83], v[82:83], v[92:93]
	v_pk_mul_f32 v[80:81], v[80:81], v[94:95]
	s_waitcnt lgkmcnt(0)
	v_add_f32_e32 v92, v104, v105
	ds_bpermute_b32 v93, v146, v92
	v_cvt_pk_bf16_f32 v80, v80, v81
	v_cvt_pk_bf16_f32 v81, v82, v83
	v_pk_mul_f32 v[82:83], v[106:107], v[90:91] op_sel_hi:[0,1]
	v_pk_mul_f32 v[82:83], v[84:85], v[82:83]
	s_waitcnt lgkmcnt(0)
	v_add_f32_e32 v90, v92, v93
	ds_bpermute_b32 v91, v147, v90
	v_pk_mul_f32 v[84:85], v[106:107], v[88:89] op_sel_hi:[0,1]
	v_pk_mul_f32 v[84:85], v[86:87], v[84:85]
	v_cvt_pk_bf16_f32 v82, v82, v83
	v_cvt_pk_bf16_f32 v83, v84, v85
	ds_write_b128 v154, v[80:83] offset:32768
	s_waitcnt lgkmcnt(1)
	v_add_f32_e32 v80, v90, v91
	v_fmamk_f32 v80, v80, 0x3c000000, v141
	v_rsq_f32_e32 v88, v80
	ds_read_b128 v[80:83], v153
	ds_read_b128 v[84:87], v153 offset:16
	v_pk_mul_f32 v[90:91], v[88:89], v[126:127] op_sel_hi:[0,1]
	s_waitcnt lgkmcnt(1)
	v_pk_mul_f32 v[80:81], v[80:81], v[90:91]
	v_pk_mul_f32 v[90:91], v[88:89], v[124:125] op_sel_hi:[0,1]
	v_pk_mul_f32 v[82:83], v[82:83], v[90:91]
	v_cvt_pk_bf16_f32 v80, v80, v81
	v_cvt_pk_bf16_f32 v81, v82, v83
	v_pk_mul_f32 v[82:83], v[88:89], v[110:111] op_sel_hi:[0,1]
	s_waitcnt lgkmcnt(0)
	v_pk_mul_f32 v[82:83], v[84:85], v[82:83]
	v_pk_mul_f32 v[84:85], v[88:89], v[108:109] op_sel_hi:[0,1]
	v_pk_mul_f32 v[84:85], v[86:87], v[84:85]
	v_cvt_pk_bf16_f32 v82, v82, v83
	v_cvt_pk_bf16_f32 v83, v84, v85
	ds_write_b128 v154, v[80:83] offset:40960
	s_waitcnt vmcnt(1)
	ds_write_b128 v156, v[96:99]
	s_waitcnt vmcnt(0)
	ds_write_b128 v157, v[100:103]
	s_branch .LBB0_1365
